# deferred weight transposes: layer weights needed late are converted f32->bf16 by the workgroups idle in the last tile round of GEMM phases 2/7/10 (nt loads/stores), P0 converts only the first 16384 it
# speedup vs baseline: 1.0285x; 1.0250x over previous
.LBB0_19:
	s_load_dwordx16 s[4:19], s[0:1], 0x0
	s_lshr_b32 s93, s92, 6
	s_cmp_lt_i32 s78, 1
	s_mov_b32 s2, 0
	s_waitcnt lgkmcnt(0)
	v_writelane_b32 v244, s4, 3
	s_nop 1
	v_writelane_b32 v244, s5, 4
	v_writelane_b32 v244, s6, 5
	v_writelane_b32 v244, s7, 6
	v_writelane_b32 v244, s8, 7
	v_writelane_b32 v244, s9, 8
	v_writelane_b32 v244, s10, 9
	v_writelane_b32 v244, s11, 10
	v_writelane_b32 v244, s12, 11
	v_writelane_b32 v244, s13, 12
	v_writelane_b32 v244, s14, 13
	v_writelane_b32 v244, s15, 14
	v_writelane_b32 v244, s16, 15
	v_writelane_b32 v244, s17, 16
	v_writelane_b32 v244, s18, 17
	v_writelane_b32 v244, s19, 18
	s_load_dwordx16 s[4:19], s[0:1], 0x40
	s_waitcnt lgkmcnt(0)
	v_writelane_b32 v244, s4, 19
	s_nop 1
	v_writelane_b32 v244, s5, 20
	v_writelane_b32 v245, s4, 0
	v_writelane_b32 v245, s5, 1
	v_writelane_b32 v244, s6, 21
	v_writelane_b32 v244, s7, 22
	v_writelane_b32 v244, s8, 23
	v_writelane_b32 v244, s9, 24
	v_writelane_b32 v244, s10, 25
	v_writelane_b32 v244, s11, 26
	v_writelane_b32 v244, s12, 27
	v_writelane_b32 v244, s13, 28
	v_writelane_b32 v244, s14, 29
	v_writelane_b32 v244, s15, 30
	v_writelane_b32 v244, s16, 31
	v_writelane_b32 v244, s17, 32
	v_writelane_b32 v244, s18, 33
	v_writelane_b32 v244, s19, 34
	s_load_dwordx16 s[4:19], s[0:1], 0x80
	s_cselect_b64 s[0:1], -1, 0
	s_cmp_gt_i32 s79, 0
	s_waitcnt lgkmcnt(0)
	v_writelane_b32 v244, s4, 35
	s_nop 1
	v_writelane_b32 v244, s5, 36
	v_writelane_b32 v244, s6, 37
	v_writelane_b32 v244, s7, 38
	v_writelane_b32 v244, s8, 39
	v_writelane_b32 v244, s9, 40
	v_writelane_b32 v244, s10, 41
	v_writelane_b32 v244, s11, 42
	v_writelane_b32 v244, s12, 43
	v_writelane_b32 v244, s13, 44
	v_writelane_b32 v244, s14, 45
	v_writelane_b32 v244, s15, 46
	v_writelane_b32 v244, s16, 47
	v_writelane_b32 v244, s17, 48
	v_writelane_b32 v244, s18, 49
	v_writelane_b32 v244, s19, 50
	v_writelane_b32 v244, s2, 51
	s_cselect_b64 s[2:3], -1, 0
	s_and_b64 s[0:1], s[0:1], s[2:3]
	s_andn2_b64 vcc, exec, s[0:1]
	s_mov_b32 s0, 0
	v_writelane_b32 v244, s0, 52
	s_cbranch_vccnz .LBB0_211
	v_mbcnt_hi_u32_b32 v7, -1, v212
	v_and_b32_e32 v65, 63, v7
	s_cmpk_gt_u32 s92, 0x27ff
	v_bfi_b32 v56, 63, v7, s92
	s_cbranch_scc1 .LBB0_24
	s_lshl_b32 s0, s93, 8
	v_readlane_b32 s4, v244, 3
	s_add_i32 s0, s0, 0
	v_readlane_b32 s6, v244, 5
	v_readlane_b32 s7, v244, 6
	v_readlane_b32 s10, v244, 9
	v_readlane_b32 s11, v244, 10
	v_lshl_add_u32 v2, v65, 2, s0
	s_mov_b64 s[0:1], 0
	s_movk_i32 s2, 0x2000
	v_mov_b32_e32 v3, s11
	v_mov_b32_e32 v4, s7
	v_mov_b32_e32 v5, s10
	v_mov_b32_e32 v6, s6
	v_mov_b32_e32 v1, 0
	s_movk_i32 s3, 0x25ff
	v_mov_b32_e32 v8, v56
	v_readlane_b32 s5, v244, 4
	v_readlane_b32 s8, v244, 7
	v_readlane_b32 s9, v244, 8
	v_readlane_b32 s12, v244, 11
	v_readlane_b32 s13, v244, 12
	v_readlane_b32 s14, v244, 13
	v_readlane_b32 s15, v244, 14
	v_readlane_b32 s16, v244, 15
	v_readlane_b32 s17, v244, 16
	v_readlane_b32 s18, v244, 17
	v_readlane_b32 s19, v244, 18

.LBB0_73:
	s_mov_b32 s99, 0xc800
	s_cmp_eq_u32 s87, 0x100
	s_cselect_b32 s99, 0x4000, s99
	s_add_i32 s98, s99, -1
	s_lshl_b32 s0, s96, 3
	s_add_i32 s20, s93, s0
	s_cmp_gt_i32 s20, s98
	s_waitcnt lgkmcnt(0)
	s_barrier
	s_cbranch_scc1 .LBB0_158
	s_cmpk_gt_i32 s20, 0x1fff
	s_cbranch_scc0 .LBB0_80
	s_cmpk_gt_u32 s20, 0x27ff
	s_cbranch_scc0 .LBB0_81
	s_cmpk_gt_u32 s20, 0x3fff
	s_cbranch_scc0 .LBB0_82
	s_cmpk_gt_u32 s20, 0x47ff
	s_cbranch_scc0 .LBB0_83
	s_cmpk_gt_u32 s20, 0x87ff
	s_cbranch_scc0 .LBB0_84
	v_readlane_b32 s36, v244, 19
	s_add_i32 s4, s20, 0xffff7800
	v_readlane_b32 s37, v244, 20
	s_lshr_b32 s0, s4, 13
	s_mov_b32 s1, 0
	v_readlane_b32 s38, v244, 21
	v_readlane_b32 s39, v244, 22
	v_readlane_b32 s40, v244, 23
	v_readlane_b32 s41, v244, 24
	v_readlane_b32 s42, v244, 25
	v_readlane_b32 s43, v244, 26
	s_mov_b64 s[12:13], s[36:37]
	s_lshl_b64 s[2:3], s[0:1], 26
	s_mov_b64 s[14:15], s[38:39]
	s_add_u32 s2, s14, s2
	s_addc_u32 s3, s15, s3
	s_lshl_b64 s[0:1], s[0:1], 25
	s_add_u32 s0, s76, s0
	s_addc_u32 s1, s77, s1
	s_add_u32 s0, s0, 0x8989000
	v_readlane_b32 s44, v244, 27
	v_readlane_b32 s45, v244, 28
	v_readlane_b32 s46, v244, 29
	v_readlane_b32 s47, v244, 30
	v_readlane_b32 s48, v244, 31
	v_readlane_b32 s49, v244, 32
	v_readlane_b32 s50, v244, 33
	v_readlane_b32 s51, v244, 34
	s_mov_b64 s[16:17], s[40:41]
	s_mov_b64 s[18:19], s[42:43]
	s_addc_u32 s1, s1, 0
	s_and_b32 s21, s4, 0x1fff
	s_mov_b64 s[4:5], 0
	s_branch .LBB0_85

.LBB0_101:
	s_add_i32 s35, s20, s24
	s_cmp_lt_i32 s35, s99
	s_cselect_b64 s[14:15], -1, 0
	s_cmp_gt_i32 s35, s98
	s_mov_b64 s[12:13], s[0:1]
	s_mov_b32 s30, s23
	s_mov_b32 s34, s22
	s_mov_b32 s31, s25
	s_mov_b32 s33, s21
	s_cbranch_scc1 .LBB0_120
	s_cmpk_lt_i32 s35, 0x2000
	s_movk_i32 s34, 0x2000
	s_cbranch_scc1 .LBB0_110
	s_cmpk_gt_u32 s35, 0x27ff
	s_cbranch_scc0 .LBB0_111
	s_cmpk_gt_u32 s35, 0x3fff
	s_cbranch_scc0 .LBB0_112
	s_cmpk_gt_u32 s35, 0x47ff
	s_cbranch_scc0 .LBB0_113
	s_cmpk_gt_u32 s35, 0x87ff
	s_mov_b64 s[18:19], -1
	s_cbranch_scc0 .LBB0_108
	s_add_i32 s18, s35, 0xffff7800
	s_lshr_b32 s2, s18, 13
	v_readlane_b32 s36, v244, 19
	s_lshl_b64 s[12:13], s[2:3], 26
	v_readlane_b32 s38, v244, 21
	v_readlane_b32 s39, v244, 22
	s_add_u32 s16, s38, s12
	s_addc_u32 s17, s39, s13
	s_lshl_b64 s[12:13], s[2:3], 25
	s_add_u32 s12, s26, s12
	v_readlane_b32 s37, v244, 20
	v_readlane_b32 s40, v244, 23
	v_readlane_b32 s41, v244, 24
	v_readlane_b32 s42, v244, 25
	v_readlane_b32 s43, v244, 26
	v_readlane_b32 s44, v244, 27
	v_readlane_b32 s45, v244, 28
	v_readlane_b32 s46, v244, 29
	v_readlane_b32 s47, v244, 30
	v_readlane_b32 s48, v244, 31
	v_readlane_b32 s49, v244, 32
	v_readlane_b32 s50, v244, 33
	v_readlane_b32 s51, v244, 34
	s_addc_u32 s13, s27, s13
	s_and_b32 s33, s18, 0x1fff
	s_mov_b64 s[18:19], 0

.LBB0_120:
	s_lshr_b32 s2, s22, 5
	v_cvt_f32_u32_e32 v68, s2
	s_sub_i32 s18, 0, s2
	s_abs_i32 s17, s21
	s_ashr_i32 s16, s21, 31
	v_rcp_iflag_f32_e32 v68, v68
	v_add_u32_e32 v83, 0x420, v82
	v_add_u32_e32 v96, 0x428, v82
	v_add_u32_e32 v84, 0x840, v82
	v_mul_f32_e32 v68, 0x4f7ffffe, v68
	v_cvt_u32_f32_e32 v68, v68
	v_add_u32_e32 v85, 0x848, v82
	v_add_u32_e32 v86, 0xc60, v82
	v_add_u32_e32 v87, 0xc68, v82
	v_readfirstlane_b32 s19, v68
	s_mul_i32 s18, s18, s19
	s_mul_hi_u32 s18, s19, s18
	s_add_i32 s19, s19, s18
	s_mul_hi_u32 s18, s17, s19
	s_mul_i32 s19, s18, s2
	s_sub_i32 s17, s17, s19
	s_add_i32 s36, s18, 1
	s_sub_i32 s19, s17, s2
	s_cmp_ge_u32 s17, s2
	s_cselect_b32 s18, s36, s18
	s_cselect_b32 s17, s19, s17
	s_add_i32 s19, s18, 1
	v_add_u32_e32 v88, 0x1080, v82
	v_add_u32_e32 v89, 0x1088, v82
	v_add_u32_e32 v90, 0x14a0, v82
	v_add_u32_e32 v91, 0x14a8, v82
	v_add_u32_e32 v92, 0x18c0, v82
	v_add_u32_e32 v93, 0x18c8, v82
	v_add_u32_e32 v94, 0x1ce0, v82
	v_add_u32_e32 v95, 0x1ce8, v82
	s_waitcnt vmcnt(7)
	ds_write2_b32 v82, v0, v1 offset1:1
	ds_write2_b32 v82, v2, v3 offset0:2 offset1:3
	s_waitcnt vmcnt(6)
	ds_write2_b32 v83, v4, v5 offset1:1
	s_cmp_ge_u32 s17, s2
	ds_write2_b32 v96, v6, v7 offset1:1
	s_waitcnt vmcnt(5)
	ds_write2_b32 v84, v8, v9 offset1:1
	ds_write2_b32 v85, v10, v11 offset1:1
	s_waitcnt vmcnt(4)
	ds_write2_b32 v86, v12, v13 offset1:1
	ds_write2_b32 v87, v14, v15 offset1:1
	s_waitcnt vmcnt(3)
	ds_write2_b32 v88, v16, v17 offset1:1
	ds_write2_b32 v89, v18, v19 offset1:1
	s_waitcnt vmcnt(2)
	ds_write2_b32 v90, v20, v21 offset1:1
	ds_write2_b32 v91, v22, v23 offset1:1
	s_waitcnt vmcnt(1)
	ds_write2_b32 v92, v24, v25 offset1:1
	ds_write2_b32 v93, v26, v27 offset1:1
	s_waitcnt vmcnt(0)
	ds_write2_b32 v94, v28, v29 offset1:1
	ds_write2_b32 v95, v30, v31 offset1:1
	s_cselect_b32 s17, s19, s18
	s_waitcnt lgkmcnt(0)
	s_xor_b32 s17, s17, s16
	ds_read2_b32 v[68:69], v81 offset1:33
	ds_read2_b32 v[70:71], v81 offset0:66 offset1:99
	ds_read2_b32 v[72:73], v81 offset0:132 offset1:165
	ds_read2_b32 v[74:75], v81 offset0:198 offset1:231
	s_sub_i32 s18, s17, s16
	s_mul_i32 s2, s18, s2
	s_sub_i32 s2, s21, s2
	s_lshl_b32 s2, s2, 5
	s_and_b32 s16, s2, 0xffffff80
	v_or_b32_e32 v98, s2, v76
	v_or_b32_e32 v97, s16, v80
	v_cmp_gt_i32_e32 vcc, s25, v98
	s_and_saveexec_b64 s[16:17], vcc
	v_and_b32_e32 v98, 0x67, v98
	v_lshlrev_b32_e32 v99, 1, v98
	v_and_b32_e32 v100, 0xc8, v99
	v_add_u32_e32 v100, 0xffffff84, v100
	v_and_b32_e32 v99, 0x48, v99
	v_cmp_gt_u32_e32 vcc, 64, v98
	s_nop 1
	v_cndmask_b32_e32 v98, v100, v99, vcc
	v_or_b32_e32 v98, v98, v97
	s_or_b64 exec, exec, s[16:17]
	s_lshl_b32 s16, s18, 6
	s_waitcnt lgkmcnt(3)
	v_cvt_pk_bf16_f32 v100, v68, v69
	v_mad_u64_u32 v[68:69], s[18:19], v98, s23, 0
	s_waitcnt lgkmcnt(2)
	v_cvt_pk_bf16_f32 v101, v70, v71
	v_ashrrev_i32_e32 v71, 31, v98
	v_mov_b32_e32 v70, v69
	v_mad_u64_u32 v[70:71], s[18:19], v71, s23, v[70:71]
	v_mov_b32_e32 v69, v70
	s_ashr_i32 s17, s16, 31
	v_lshl_add_u64 v[68:69], v[68:69], 1, s[0:1]
	s_waitcnt lgkmcnt(1)
	v_cvt_pk_bf16_f32 v102, v72, v73
	s_waitcnt lgkmcnt(0)
	v_cvt_pk_bf16_f32 v103, v74, v75
	v_lshl_add_u64 v[98:99], s[16:17], 1, v[68:69]
	ds_read2_b32 v[68:69], v81 offset0:8 offset1:41
	ds_read2_b32 v[70:71], v81 offset0:74 offset1:107
	ds_read2_b32 v[72:73], v81 offset0:140 offset1:173
	ds_read2_b32 v[74:75], v81 offset0:206 offset1:239
	v_lshl_add_u64 v[98:99], v[98:99], 0, v[66:67]
	global_store_dwordx4 v[98:99], v[100:103], off
	v_or_b32_e32 v98, s2, v77
	v_cmp_gt_i32_e32 vcc, s25, v98
	s_and_saveexec_b64 s[18:19], vcc
	v_and_b32_e32 v98, 0x6f, v98
	v_lshlrev_b32_e32 v99, 1, v98
	v_and_b32_e32 v100, 0xd8, v99
	v_add_u32_e32 v100, 0xffffff84, v100
	v_and_b32_e32 v99, 0x58, v99
	v_cmp_gt_u32_e32 vcc, 64, v98
	s_nop 1
	v_cndmask_b32_e32 v98, v100, v99, vcc
	v_or_b32_e32 v98, v98, v97
	s_or_b64 exec, exec, s[18:19]
	s_waitcnt lgkmcnt(3)
	v_cvt_pk_bf16_f32 v100, v68, v69
	v_mad_u64_u32 v[68:69], s[18:19], v98, s23, 0
	s_waitcnt lgkmcnt(2)
	v_cvt_pk_bf16_f32 v101, v70, v71
	v_ashrrev_i32_e32 v71, 31, v98
	v_mov_b32_e32 v70, v69
	v_mad_u64_u32 v[70:71], s[18:19], v71, s23, v[70:71]
	v_mov_b32_e32 v69, v70
	v_lshl_add_u64 v[68:69], v[68:69], 1, s[0:1]
	s_waitcnt lgkmcnt(1)
	v_cvt_pk_bf16_f32 v102, v72, v73
	s_waitcnt lgkmcnt(0)
	v_cvt_pk_bf16_f32 v103, v74, v75
	v_lshl_add_u64 v[98:99], s[16:17], 1, v[68:69]
	ds_read2_b32 v[68:69], v81 offset0:16 offset1:49
	ds_read2_b32 v[70:71], v81 offset0:82 offset1:115
	ds_read2_b32 v[72:73], v81 offset0:148 offset1:181
	ds_read2_b32 v[74:75], v81 offset0:214 offset1:247
	v_lshl_add_u64 v[98:99], v[98:99], 0, v[66:67]
	global_store_dwordx4 v[98:99], v[100:103], off
	v_or_b32_e32 v98, s2, v78
	v_cmp_gt_i32_e32 vcc, s25, v98
	s_and_saveexec_b64 s[18:19], vcc
	v_and_b32_e32 v98, 0x77, v98
	v_lshlrev_b32_e32 v99, 1, v98
	v_and_b32_e32 v100, 0xe8, v99
	v_add_u32_e32 v100, 0xffffff84, v100
	v_and_b32_e32 v99, 0x68, v99
	v_cmp_gt_u32_e32 vcc, 64, v98
	s_nop 1
	v_cndmask_b32_e32 v98, v100, v99, vcc
	v_or_b32_e32 v98, v98, v97
	s_or_b64 exec, exec, s[18:19]
	s_waitcnt lgkmcnt(3)
	v_cvt_pk_bf16_f32 v100, v68, v69
	v_mad_u64_u32 v[68:69], s[18:19], v98, s23, 0
	s_waitcnt lgkmcnt(2)
	v_cvt_pk_bf16_f32 v101, v70, v71
	v_ashrrev_i32_e32 v71, 31, v98
	v_mov_b32_e32 v70, v69
	v_mad_u64_u32 v[70:71], s[18:19], v71, s23, v[70:71]
	v_mov_b32_e32 v69, v70
	v_lshl_add_u64 v[68:69], v[68:69], 1, s[0:1]
	s_waitcnt lgkmcnt(1)
	v_cvt_pk_bf16_f32 v102, v72, v73
	s_waitcnt lgkmcnt(0)
	v_cvt_pk_bf16_f32 v103, v74, v75
	v_lshl_add_u64 v[98:99], s[16:17], 1, v[68:69]
	ds_read2_b32 v[68:69], v81 offset0:24 offset1:57
	ds_read2_b32 v[70:71], v81 offset0:90 offset1:123
	ds_read2_b32 v[72:73], v81 offset0:156 offset1:189
	ds_read2_b32 v[74:75], v81 offset0:222 offset1:255
	v_lshl_add_u64 v[98:99], v[98:99], 0, v[66:67]
	global_store_dwordx4 v[98:99], v[100:103], off
	v_or_b32_e32 v98, s2, v79
	v_cmp_gt_i32_e32 vcc, s25, v98
	s_and_saveexec_b64 s[18:19], vcc
	v_and_b32_e32 v98, 0x7f, v98
	v_lshlrev_b32_e32 v99, 1, v98
	v_and_b32_e32 v100, 0xf8, v99
	v_add_u32_e32 v100, 0xffffff84, v100
	v_and_b32_e32 v99, 0x78, v99
	v_cmp_gt_u32_e32 vcc, 64, v98
	s_nop 1
	v_cndmask_b32_e32 v98, v100, v99, vcc
	v_or_b32_e32 v98, v98, v97
	s_or_b64 exec, exec, s[18:19]
	s_waitcnt lgkmcnt(3)
	v_cvt_pk_bf16_f32 v68, v68, v69
	s_waitcnt lgkmcnt(2)
	v_cvt_pk_bf16_f32 v69, v70, v71
	s_waitcnt lgkmcnt(1)
	v_cvt_pk_bf16_f32 v70, v72, v73
	v_mad_u64_u32 v[72:73], s[18:19], v98, s23, 0
	s_waitcnt lgkmcnt(0)
	v_cvt_pk_bf16_f32 v71, v74, v75
	v_ashrrev_i32_e32 v75, 31, v98
	v_mov_b32_e32 v74, v73
	v_mad_u64_u32 v[74:75], s[18:19], v75, s23, v[74:75]
	v_mov_b32_e32 v73, v74
	v_lshl_add_u64 v[72:73], v[72:73], 1, s[0:1]
	v_lshl_add_u64 v[72:73], s[16:17], 1, v[72:73]
	v_lshl_add_u64 v[72:73], v[72:73], 0, v[66:67]
	global_store_dwordx4 v[72:73], v[68:71], off
	s_waitcnt lgkmcnt(0)
	s_andn2_b64 vcc, exec, s[14:15]
	s_mov_b64 s[14:15], 0
	s_cbranch_vccnz .LBB0_100
	s_add_i32 s35, s35, s24
	s_cmp_lt_i32 s35, s99
	s_cselect_b64 s[14:15], -1, 0
	s_cmp_gt_i32 s35, s98
	s_cbranch_scc1 .LBB0_149
	s_cmpk_lt_i32 s35, 0x2000
	s_movk_i32 s22, 0x2000
	s_cbranch_scc1 .LBB0_138
	s_cmpk_gt_u32 s35, 0x27ff
	s_cbranch_scc0 .LBB0_139
	s_cmpk_gt_u32 s35, 0x3fff
	s_cbranch_scc0 .LBB0_140
	s_cmpk_gt_u32 s35, 0x47ff
	s_cbranch_scc0 .LBB0_142
	s_cmpk_gt_u32 s35, 0x87ff
	s_mov_b64 s[18:19], -1
	s_cbranch_scc0 .LBB0_136
	s_add_i32 s18, s35, 0xffff7800
	s_lshr_b32 s2, s18, 13
	v_readlane_b32 s36, v244, 19
	s_lshl_b64 s[0:1], s[2:3], 26
	v_readlane_b32 s38, v244, 21
	v_readlane_b32 s39, v244, 22
	s_add_u32 s16, s38, s0
	s_addc_u32 s17, s39, s1
	s_lshl_b64 s[0:1], s[2:3], 25
	s_add_u32 s0, s26, s0
	v_readlane_b32 s37, v244, 20
	v_readlane_b32 s40, v244, 23
	v_readlane_b32 s41, v244, 24
	v_readlane_b32 s42, v244, 25
	v_readlane_b32 s43, v244, 26
	v_readlane_b32 s44, v244, 27
	v_readlane_b32 s45, v244, 28
	v_readlane_b32 s46, v244, 29
	v_readlane_b32 s47, v244, 30
	v_readlane_b32 s48, v244, 31
	v_readlane_b32 s49, v244, 32
	v_readlane_b32 s50, v244, 33
	v_readlane_b32 s51, v244, 34
	s_addc_u32 s1, s27, s1
	s_and_b32 s21, s18, 0x1fff
	s_mov_b64 s[18:19], 0

.LBB0_363:
	s_waitcnt vmcnt(0)
	s_barrier
	s_cmp_lg_u32 s87, 0x100
	s_cbranch_scc1 .Ltt2_done
	s_cmp_lt_u32 s96, 128
	s_cbranch_scc1 .Ltt2_done
	s_sub_u32 s20, s96, 128
	s_lshl_b32 s20, s20, 3
	s_add_u32 s20, s20, s93
	s_movk_i32 s23, 1024
	v_mbcnt_hi_u32_b32 v0, -1, v212
	v_and_b32_e32 v0, 63, v0
	v_lshrrev_b32_e32 v1, 3, v0
	v_and_b32_e32 v2, 7, v0
	s_lshl_b32 s25, s93, 14
	v_mul_u32_u24_e32 v3, 0x84, v1
	v_mul_u32_u24_e32 v4, 0x420, v2
	v_lshlrev_b32_e32 v2, 4, v2
	v_add3_u32 v3, v3, v2, s25
	v_lshl_add_u32 v4, v1, 2, v4
	v_add_u32_e32 v4, s25, v4
	v_readlane_b32 s62, v245, 0
	v_readlane_b32 s63, v245, 1
	s_add_u32 s64, s76, 0x4989000
	s_addc_u32 s65, s77, 0
	v_readlane_b32 s66, v244, 21
	v_readlane_b32 s67, v244, 22
	s_add_u32 s68, s76, 0x8989000
	s_addc_u32 s69, s77, 0
	s_cmp_ge_u32 s20, 12288
	s_cbranch_scc1 .Ltt2_done
	s_cmp_lt_u32 s20, 8192
	s_cbranch_scc1 .Ltt2_r1_s0
	s_sub_u32 s25, s20, 8192
	s_lshr_b32 s27, s25, 6
	s_and_b32 s31, s25, 63
	s_mul_i32 s35, s27, 0x80000
	s_lshl_b32 s41, s31, 7
	s_add_u32 s35, s35, s41
	s_add_u32 s0, s66, s35
	s_addc_u32 s1, s67, 0
	s_mul_i32 s35, s31, 0x80000
	s_lshl_b32 s41, s27, 7
	s_add_u32 s35, s35, s41
	s_add_u32 s2, s68, s35
	s_addc_u32 s3, s69, 0
	s_mov_b32 s5, 0x2000
	s_mov_b32 s6, 0x10000
	s_mov_b32 s7, 0x4000
	s_branch .Ltt2_r1_e
.Ltt2_r1_s0:
	s_sub_u32 s25, s20, 0
	s_lshr_b32 s27, s25, 8
	s_and_b32 s31, s25, 255
	s_mul_i32 s35, s27, 0x200000
	s_lshl_b32 s41, s31, 7
	s_add_u32 s35, s35, s41
	s_add_u32 s0, s62, s35
	s_addc_u32 s1, s63, 0
	s_mul_i32 s35, s31, 0x20000
	s_lshl_b32 s41, s27, 7
	s_add_u32 s35, s35, s41
	s_add_u32 s2, s64, s35
	s_addc_u32 s3, s65, 0
	s_mov_b32 s5, 0x8000
	s_mov_b32 s6, 0x40000
	s_mov_b32 s7, 0x1000
.Ltt2_r1_e:
	v_mad_u32_u24 v5, v1, s5, v2
	global_load_dwordx4 v[8:11], v5, s[0:1] nt
	s_add_u32 s0, s0, s6
	s_addc_u32 s1, s1, 0
	global_load_dwordx4 v[12:15], v5, s[0:1] nt
	s_add_u32 s0, s0, s6
	s_addc_u32 s1, s1, 0
	global_load_dwordx4 v[16:19], v5, s[0:1] nt
	s_add_u32 s0, s0, s6
	s_addc_u32 s1, s1, 0
	global_load_dwordx4 v[20:23], v5, s[0:1] nt
	s_add_u32 s0, s0, s6
	s_addc_u32 s1, s1, 0
	global_load_dwordx4 v[24:27], v5, s[0:1] nt
	s_add_u32 s0, s0, s6
	s_addc_u32 s1, s1, 0
	global_load_dwordx4 v[28:31], v5, s[0:1] nt
	s_add_u32 s0, s0, s6
	s_addc_u32 s1, s1, 0
	global_load_dwordx4 v[32:35], v5, s[0:1] nt
	s_add_u32 s0, s0, s6
	s_addc_u32 s1, s1, 0
	global_load_dwordx4 v[36:39], v5, s[0:1] nt
	s_add_u32 s0, s0, s6
	s_addc_u32 s1, s1, 0
	s_add_u32 s20, s20, s23
	s_cmp_ge_u32 s20, 12288
	s_cbranch_scc1 .Ltt2_lastA0
	s_cmp_lt_u32 s20, 8192
	s_cbranch_scc1 .Ltt2_r2_s0
	s_sub_u32 s25, s20, 8192
	s_lshr_b32 s27, s25, 6
	s_and_b32 s31, s25, 63
	s_mul_i32 s35, s27, 0x80000
	s_lshl_b32 s41, s31, 7
	s_add_u32 s35, s35, s41
	s_add_u32 s0, s66, s35
	s_addc_u32 s1, s67, 0
	s_mul_i32 s35, s31, 0x80000
	s_lshl_b32 s41, s27, 7
	s_add_u32 s35, s35, s41
	s_add_u32 s10, s68, s35
	s_addc_u32 s11, s69, 0
	s_mov_b32 s5, 0x2000
	s_mov_b32 s6, 0x10000
	s_mov_b32 s47, 0x4000
	s_branch .Ltt2_r2_e
.Ltt2_r2_s0:
	s_sub_u32 s25, s20, 0
	s_lshr_b32 s27, s25, 8
	s_and_b32 s31, s25, 255
	s_mul_i32 s35, s27, 0x200000
	s_lshl_b32 s41, s31, 7
	s_add_u32 s35, s35, s41
	s_add_u32 s0, s62, s35
	s_addc_u32 s1, s63, 0
	s_mul_i32 s35, s31, 0x20000
	s_lshl_b32 s41, s27, 7
	s_add_u32 s35, s35, s41
	s_add_u32 s10, s64, s35
	s_addc_u32 s11, s65, 0
	s_mov_b32 s5, 0x8000
	s_mov_b32 s6, 0x40000
	s_mov_b32 s47, 0x1000
.Ltt2_r2_e:
	v_mad_u32_u24 v5, v1, s5, v2
	global_load_dwordx4 v[40:43], v5, s[0:1] nt
	s_add_u32 s0, s0, s6
	s_addc_u32 s1, s1, 0
	global_load_dwordx4 v[44:47], v5, s[0:1] nt
	s_add_u32 s0, s0, s6
	s_addc_u32 s1, s1, 0
	global_load_dwordx4 v[48:51], v5, s[0:1] nt
	s_add_u32 s0, s0, s6
	s_addc_u32 s1, s1, 0
	global_load_dwordx4 v[52:55], v5, s[0:1] nt
	s_add_u32 s0, s0, s6
	s_addc_u32 s1, s1, 0
	global_load_dwordx4 v[56:59], v5, s[0:1] nt
	s_add_u32 s0, s0, s6
	s_addc_u32 s1, s1, 0
	global_load_dwordx4 v[60:63], v5, s[0:1] nt
	s_add_u32 s0, s0, s6
	s_addc_u32 s1, s1, 0
	global_load_dwordx4 v[64:67], v5, s[0:1] nt
	s_add_u32 s0, s0, s6
	s_addc_u32 s1, s1, 0
	global_load_dwordx4 v[68:71], v5, s[0:1] nt
	s_add_u32 s0, s0, s6
	s_addc_u32 s1, s1, 0
	s_waitcnt vmcnt(8)
	ds_write_b32 v3, v8 offset:0
	ds_write_b32 v3, v9 offset:4
	ds_write_b32 v3, v10 offset:8
	ds_write_b32 v3, v11 offset:12
	ds_write_b32 v3, v12 offset:1056
	ds_write_b32 v3, v13 offset:1060
	ds_write_b32 v3, v14 offset:1064
	ds_write_b32 v3, v15 offset:1068
	ds_write_b32 v3, v16 offset:2112
	ds_write_b32 v3, v17 offset:2116
	ds_write_b32 v3, v18 offset:2120
	ds_write_b32 v3, v19 offset:2124
	ds_write_b32 v3, v20 offset:3168
	ds_write_b32 v3, v21 offset:3172
	ds_write_b32 v3, v22 offset:3176
	ds_write_b32 v3, v23 offset:3180
	ds_write_b32 v3, v24 offset:4224
	ds_write_b32 v3, v25 offset:4228
	ds_write_b32 v3, v26 offset:4232
	ds_write_b32 v3, v27 offset:4236
	ds_write_b32 v3, v28 offset:5280
	ds_write_b32 v3, v29 offset:5284
	ds_write_b32 v3, v30 offset:5288
	ds_write_b32 v3, v31 offset:5292
	ds_write_b32 v3, v32 offset:6336
	ds_write_b32 v3, v33 offset:6340
	ds_write_b32 v3, v34 offset:6344
	ds_write_b32 v3, v35 offset:6348
	ds_write_b32 v3, v36 offset:7392
	ds_write_b32 v3, v37 offset:7396
	ds_write_b32 v3, v38 offset:7400
	ds_write_b32 v3, v39 offset:7404
	s_mov_b32 s32, s2
	s_mov_b32 s33, s3
	s_lshl_b32 s49, s7, 3
	v_mad_u32_u24 v6, v1, s7, v2
	s_waitcnt lgkmcnt(0)
	ds_read_b32 v72, v4 offset:0
	ds_read_b32 v73, v4 offset:132
	ds_read_b32 v74, v4 offset:264
	ds_read_b32 v75, v4 offset:396
	ds_read_b32 v76, v4 offset:528
	ds_read_b32 v77, v4 offset:660
	ds_read_b32 v78, v4 offset:792
	ds_read_b32 v79, v4 offset:924
	ds_read_b32 v80, v4 offset:32
	ds_read_b32 v81, v4 offset:164
	ds_read_b32 v82, v4 offset:296
	ds_read_b32 v83, v4 offset:428
	ds_read_b32 v84, v4 offset:560
	ds_read_b32 v85, v4 offset:692
	ds_read_b32 v86, v4 offset:824
	ds_read_b32 v87, v4 offset:956
	s_waitcnt lgkmcnt(8)
	v_cvt_pk_bf16_f32 v104, v72, v73
	v_cvt_pk_bf16_f32 v105, v74, v75
	v_cvt_pk_bf16_f32 v106, v76, v77
	v_cvt_pk_bf16_f32 v107, v78, v79
	global_store_dwordx4 v6, v[104:107], s[32:33] nt
	s_add_u32 s32, s32, s49
	s_addc_u32 s33, s33, 0
	ds_read_b32 v88, v4 offset:64
	ds_read_b32 v89, v4 offset:196
	ds_read_b32 v90, v4 offset:328
	ds_read_b32 v91, v4 offset:460
	ds_read_b32 v92, v4 offset:592
	ds_read_b32 v93, v4 offset:724
	ds_read_b32 v94, v4 offset:856
	ds_read_b32 v95, v4 offset:988
	s_waitcnt lgkmcnt(8)
	v_cvt_pk_bf16_f32 v108, v80, v81
	v_cvt_pk_bf16_f32 v109, v82, v83
	v_cvt_pk_bf16_f32 v110, v84, v85
	v_cvt_pk_bf16_f32 v111, v86, v87
	global_store_dwordx4 v6, v[108:111], s[32:33] nt
	s_add_u32 s32, s32, s49
	s_addc_u32 s33, s33, 0
	ds_read_b32 v96, v4 offset:96
	ds_read_b32 v97, v4 offset:228
	ds_read_b32 v98, v4 offset:360
	ds_read_b32 v99, v4 offset:492
	ds_read_b32 v100, v4 offset:624
	ds_read_b32 v101, v4 offset:756
	ds_read_b32 v102, v4 offset:888
	ds_read_b32 v103, v4 offset:1020
	s_waitcnt lgkmcnt(8)
	v_cvt_pk_bf16_f32 v112, v88, v89
	v_cvt_pk_bf16_f32 v113, v90, v91
	v_cvt_pk_bf16_f32 v114, v92, v93
	v_cvt_pk_bf16_f32 v115, v94, v95
	global_store_dwordx4 v6, v[112:115], s[32:33] nt
	s_add_u32 s32, s32, s49
	s_addc_u32 s33, s33, 0
	s_waitcnt lgkmcnt(0)
	v_cvt_pk_bf16_f32 v116, v96, v97
	v_cvt_pk_bf16_f32 v117, v98, v99
	v_cvt_pk_bf16_f32 v118, v100, v101
	v_cvt_pk_bf16_f32 v119, v102, v103
	global_store_dwordx4 v6, v[116:119], s[32:33] nt
	s_add_u32 s32, s32, s49
	s_addc_u32 s33, s33, 0
.Ltt2_loop:
	s_add_u32 s20, s20, s23
	s_cmp_ge_u32 s20, 12288
	s_cbranch_scc1 .Ltt2_lastB
	s_cmp_lt_u32 s20, 8192
	s_cbranch_scc1 .Ltt2_r3_s0
	s_sub_u32 s25, s20, 8192
	s_lshr_b32 s27, s25, 6
	s_and_b32 s31, s25, 63
	s_mul_i32 s35, s27, 0x80000
	s_lshl_b32 s41, s31, 7
	s_add_u32 s35, s35, s41
	s_add_u32 s0, s66, s35
	s_addc_u32 s1, s67, 0
	s_mul_i32 s35, s31, 0x80000
	s_lshl_b32 s41, s27, 7
	s_add_u32 s35, s35, s41
	s_add_u32 s2, s68, s35
	s_addc_u32 s3, s69, 0
	s_mov_b32 s5, 0x2000
	s_mov_b32 s6, 0x10000
	s_mov_b32 s7, 0x4000
	s_branch .Ltt2_r3_e

.Ltt2_r3_e:
	v_mad_u32_u24 v5, v1, s5, v2
	global_load_dwordx4 v[8:11], v5, s[0:1] nt
	s_add_u32 s0, s0, s6
	s_addc_u32 s1, s1, 0
	global_load_dwordx4 v[12:15], v5, s[0:1] nt
	s_add_u32 s0, s0, s6
	s_addc_u32 s1, s1, 0
	global_load_dwordx4 v[16:19], v5, s[0:1] nt
	s_add_u32 s0, s0, s6
	s_addc_u32 s1, s1, 0
	global_load_dwordx4 v[20:23], v5, s[0:1] nt
	s_add_u32 s0, s0, s6
	s_addc_u32 s1, s1, 0
	global_load_dwordx4 v[24:27], v5, s[0:1] nt
	s_add_u32 s0, s0, s6
	s_addc_u32 s1, s1, 0
	global_load_dwordx4 v[28:31], v5, s[0:1] nt
	s_add_u32 s0, s0, s6
	s_addc_u32 s1, s1, 0
	global_load_dwordx4 v[32:35], v5, s[0:1] nt
	s_add_u32 s0, s0, s6
	s_addc_u32 s1, s1, 0
	global_load_dwordx4 v[36:39], v5, s[0:1] nt
	s_add_u32 s0, s0, s6
	s_addc_u32 s1, s1, 0
	s_waitcnt vmcnt(12)
	ds_write_b32 v3, v40 offset:0
	ds_write_b32 v3, v41 offset:4
	ds_write_b32 v3, v42 offset:8
	ds_write_b32 v3, v43 offset:12
	ds_write_b32 v3, v44 offset:1056
	ds_write_b32 v3, v45 offset:1060
	ds_write_b32 v3, v46 offset:1064
	ds_write_b32 v3, v47 offset:1068
	ds_write_b32 v3, v48 offset:2112
	ds_write_b32 v3, v49 offset:2116
	ds_write_b32 v3, v50 offset:2120
	ds_write_b32 v3, v51 offset:2124
	ds_write_b32 v3, v52 offset:3168
	ds_write_b32 v3, v53 offset:3172
	ds_write_b32 v3, v54 offset:3176
	ds_write_b32 v3, v55 offset:3180
	ds_write_b32 v3, v56 offset:4224
	ds_write_b32 v3, v57 offset:4228
	ds_write_b32 v3, v58 offset:4232
	ds_write_b32 v3, v59 offset:4236
	ds_write_b32 v3, v60 offset:5280
	ds_write_b32 v3, v61 offset:5284
	ds_write_b32 v3, v62 offset:5288
	ds_write_b32 v3, v63 offset:5292
	ds_write_b32 v3, v64 offset:6336
	ds_write_b32 v3, v65 offset:6340
	ds_write_b32 v3, v66 offset:6344
	ds_write_b32 v3, v67 offset:6348
	ds_write_b32 v3, v68 offset:7392
	ds_write_b32 v3, v69 offset:7396
	ds_write_b32 v3, v70 offset:7400
	ds_write_b32 v3, v71 offset:7404
	s_mov_b32 s32, s10
	s_mov_b32 s33, s11
	s_lshl_b32 s49, s47, 3
	v_mad_u32_u24 v6, v1, s47, v2
	s_waitcnt lgkmcnt(0)
	ds_read_b32 v72, v4 offset:0
	ds_read_b32 v73, v4 offset:132
	ds_read_b32 v74, v4 offset:264
	ds_read_b32 v75, v4 offset:396
	ds_read_b32 v76, v4 offset:528
	ds_read_b32 v77, v4 offset:660
	ds_read_b32 v78, v4 offset:792
	ds_read_b32 v79, v4 offset:924
	ds_read_b32 v80, v4 offset:32
	ds_read_b32 v81, v4 offset:164
	ds_read_b32 v82, v4 offset:296
	ds_read_b32 v83, v4 offset:428
	ds_read_b32 v84, v4 offset:560
	ds_read_b32 v85, v4 offset:692
	ds_read_b32 v86, v4 offset:824
	ds_read_b32 v87, v4 offset:956
	s_waitcnt lgkmcnt(8)
	v_cvt_pk_bf16_f32 v104, v72, v73
	v_cvt_pk_bf16_f32 v105, v74, v75
	v_cvt_pk_bf16_f32 v106, v76, v77
	v_cvt_pk_bf16_f32 v107, v78, v79
	global_store_dwordx4 v6, v[104:107], s[32:33] nt
	s_add_u32 s32, s32, s49
	s_addc_u32 s33, s33, 0
	ds_read_b32 v88, v4 offset:64
	ds_read_b32 v89, v4 offset:196
	ds_read_b32 v90, v4 offset:328
	ds_read_b32 v91, v4 offset:460
	ds_read_b32 v92, v4 offset:592
	ds_read_b32 v93, v4 offset:724
	ds_read_b32 v94, v4 offset:856
	ds_read_b32 v95, v4 offset:988
	s_waitcnt lgkmcnt(8)
	v_cvt_pk_bf16_f32 v108, v80, v81
	v_cvt_pk_bf16_f32 v109, v82, v83
	v_cvt_pk_bf16_f32 v110, v84, v85
	v_cvt_pk_bf16_f32 v111, v86, v87
	global_store_dwordx4 v6, v[108:111], s[32:33] nt
	s_add_u32 s32, s32, s49
	s_addc_u32 s33, s33, 0
	ds_read_b32 v96, v4 offset:96
	ds_read_b32 v97, v4 offset:228
	ds_read_b32 v98, v4 offset:360
	ds_read_b32 v99, v4 offset:492
	ds_read_b32 v100, v4 offset:624
	ds_read_b32 v101, v4 offset:756
	ds_read_b32 v102, v4 offset:888
	ds_read_b32 v103, v4 offset:1020
	s_waitcnt lgkmcnt(8)
	v_cvt_pk_bf16_f32 v112, v88, v89
	v_cvt_pk_bf16_f32 v113, v90, v91
	v_cvt_pk_bf16_f32 v114, v92, v93
	v_cvt_pk_bf16_f32 v115, v94, v95
	global_store_dwordx4 v6, v[112:115], s[32:33] nt
	s_add_u32 s32, s32, s49
	s_addc_u32 s33, s33, 0
	s_waitcnt lgkmcnt(0)
	v_cvt_pk_bf16_f32 v116, v96, v97
	v_cvt_pk_bf16_f32 v117, v98, v99
	v_cvt_pk_bf16_f32 v118, v100, v101
	v_cvt_pk_bf16_f32 v119, v102, v103
	global_store_dwordx4 v6, v[116:119], s[32:33] nt
	s_add_u32 s32, s32, s49
	s_addc_u32 s33, s33, 0
	s_add_u32 s20, s20, s23
	s_cmp_ge_u32 s20, 12288
	s_cbranch_scc1 .Ltt2_lastA
	s_cmp_lt_u32 s20, 8192
	s_cbranch_scc1 .Ltt2_r4_s0
	s_sub_u32 s25, s20, 8192
	s_lshr_b32 s27, s25, 6
	s_and_b32 s31, s25, 63
	s_mul_i32 s35, s27, 0x80000
	s_lshl_b32 s41, s31, 7
	s_add_u32 s35, s35, s41
	s_add_u32 s0, s66, s35
	s_addc_u32 s1, s67, 0
	s_mul_i32 s35, s31, 0x80000
	s_lshl_b32 s41, s27, 7
	s_add_u32 s35, s35, s41
	s_add_u32 s10, s68, s35
	s_addc_u32 s11, s69, 0
	s_mov_b32 s5, 0x2000
	s_mov_b32 s6, 0x10000
	s_mov_b32 s47, 0x4000
	s_branch .Ltt2_r4_e

.Ltt2_r4_e:
	v_mad_u32_u24 v5, v1, s5, v2
	global_load_dwordx4 v[40:43], v5, s[0:1] nt
	s_add_u32 s0, s0, s6
	s_addc_u32 s1, s1, 0
	global_load_dwordx4 v[44:47], v5, s[0:1] nt
	s_add_u32 s0, s0, s6
	s_addc_u32 s1, s1, 0
	global_load_dwordx4 v[48:51], v5, s[0:1] nt
	s_add_u32 s0, s0, s6
	s_addc_u32 s1, s1, 0
	global_load_dwordx4 v[52:55], v5, s[0:1] nt
	s_add_u32 s0, s0, s6
	s_addc_u32 s1, s1, 0
	global_load_dwordx4 v[56:59], v5, s[0:1] nt
	s_add_u32 s0, s0, s6
	s_addc_u32 s1, s1, 0
	global_load_dwordx4 v[60:63], v5, s[0:1] nt
	s_add_u32 s0, s0, s6
	s_addc_u32 s1, s1, 0
	global_load_dwordx4 v[64:67], v5, s[0:1] nt
	s_add_u32 s0, s0, s6
	s_addc_u32 s1, s1, 0
	global_load_dwordx4 v[68:71], v5, s[0:1] nt
	s_add_u32 s0, s0, s6
	s_addc_u32 s1, s1, 0
	s_waitcnt vmcnt(12)
	ds_write_b32 v3, v8 offset:0
	ds_write_b32 v3, v9 offset:4
	ds_write_b32 v3, v10 offset:8
	ds_write_b32 v3, v11 offset:12
	ds_write_b32 v3, v12 offset:1056
	ds_write_b32 v3, v13 offset:1060
	ds_write_b32 v3, v14 offset:1064
	ds_write_b32 v3, v15 offset:1068
	ds_write_b32 v3, v16 offset:2112
	ds_write_b32 v3, v17 offset:2116
	ds_write_b32 v3, v18 offset:2120
	ds_write_b32 v3, v19 offset:2124
	ds_write_b32 v3, v20 offset:3168
	ds_write_b32 v3, v21 offset:3172
	ds_write_b32 v3, v22 offset:3176
	ds_write_b32 v3, v23 offset:3180
	ds_write_b32 v3, v24 offset:4224
	ds_write_b32 v3, v25 offset:4228
	ds_write_b32 v3, v26 offset:4232
	ds_write_b32 v3, v27 offset:4236
	ds_write_b32 v3, v28 offset:5280
	ds_write_b32 v3, v29 offset:5284
	ds_write_b32 v3, v30 offset:5288
	ds_write_b32 v3, v31 offset:5292
	ds_write_b32 v3, v32 offset:6336
	ds_write_b32 v3, v33 offset:6340
	ds_write_b32 v3, v34 offset:6344
	ds_write_b32 v3, v35 offset:6348
	ds_write_b32 v3, v36 offset:7392
	ds_write_b32 v3, v37 offset:7396
	ds_write_b32 v3, v38 offset:7400
	ds_write_b32 v3, v39 offset:7404
	s_mov_b32 s32, s2
	s_mov_b32 s33, s3
	s_lshl_b32 s49, s7, 3
	v_mad_u32_u24 v6, v1, s7, v2
	s_waitcnt lgkmcnt(0)
	ds_read_b32 v72, v4 offset:0
	ds_read_b32 v73, v4 offset:132
	ds_read_b32 v74, v4 offset:264
	ds_read_b32 v75, v4 offset:396
	ds_read_b32 v76, v4 offset:528
	ds_read_b32 v77, v4 offset:660
	ds_read_b32 v78, v4 offset:792
	ds_read_b32 v79, v4 offset:924
	ds_read_b32 v80, v4 offset:32
	ds_read_b32 v81, v4 offset:164
	ds_read_b32 v82, v4 offset:296
	ds_read_b32 v83, v4 offset:428
	ds_read_b32 v84, v4 offset:560
	ds_read_b32 v85, v4 offset:692
	ds_read_b32 v86, v4 offset:824
	ds_read_b32 v87, v4 offset:956
	s_waitcnt lgkmcnt(8)
	v_cvt_pk_bf16_f32 v104, v72, v73
	v_cvt_pk_bf16_f32 v105, v74, v75
	v_cvt_pk_bf16_f32 v106, v76, v77
	v_cvt_pk_bf16_f32 v107, v78, v79
	global_store_dwordx4 v6, v[104:107], s[32:33] nt
	s_add_u32 s32, s32, s49
	s_addc_u32 s33, s33, 0
	ds_read_b32 v88, v4 offset:64
	ds_read_b32 v89, v4 offset:196
	ds_read_b32 v90, v4 offset:328
	ds_read_b32 v91, v4 offset:460
	ds_read_b32 v92, v4 offset:592
	ds_read_b32 v93, v4 offset:724
	ds_read_b32 v94, v4 offset:856
	ds_read_b32 v95, v4 offset:988
	s_waitcnt lgkmcnt(8)
	v_cvt_pk_bf16_f32 v108, v80, v81
	v_cvt_pk_bf16_f32 v109, v82, v83
	v_cvt_pk_bf16_f32 v110, v84, v85
	v_cvt_pk_bf16_f32 v111, v86, v87
	global_store_dwordx4 v6, v[108:111], s[32:33] nt
	s_add_u32 s32, s32, s49
	s_addc_u32 s33, s33, 0
	ds_read_b32 v96, v4 offset:96
	ds_read_b32 v97, v4 offset:228
	ds_read_b32 v98, v4 offset:360
	ds_read_b32 v99, v4 offset:492
	ds_read_b32 v100, v4 offset:624
	ds_read_b32 v101, v4 offset:756
	ds_read_b32 v102, v4 offset:888
	ds_read_b32 v103, v4 offset:1020
	s_waitcnt lgkmcnt(8)
	v_cvt_pk_bf16_f32 v112, v88, v89
	v_cvt_pk_bf16_f32 v113, v90, v91
	v_cvt_pk_bf16_f32 v114, v92, v93
	v_cvt_pk_bf16_f32 v115, v94, v95
	global_store_dwordx4 v6, v[112:115], s[32:33] nt
	s_add_u32 s32, s32, s49
	s_addc_u32 s33, s33, 0
	s_waitcnt lgkmcnt(0)
	v_cvt_pk_bf16_f32 v116, v96, v97
	v_cvt_pk_bf16_f32 v117, v98, v99
	v_cvt_pk_bf16_f32 v118, v100, v101
	v_cvt_pk_bf16_f32 v119, v102, v103
	global_store_dwordx4 v6, v[116:119], s[32:33] nt
	s_add_u32 s32, s32, s49
	s_addc_u32 s33, s33, 0
	s_branch .Ltt2_loop
.Ltt2_lastA0:
	s_waitcnt vmcnt(0)
	ds_write_b32 v3, v8 offset:0
	ds_write_b32 v3, v9 offset:4
	ds_write_b32 v3, v10 offset:8
	ds_write_b32 v3, v11 offset:12
	ds_write_b32 v3, v12 offset:1056
	ds_write_b32 v3, v13 offset:1060
	ds_write_b32 v3, v14 offset:1064
	ds_write_b32 v3, v15 offset:1068
	ds_write_b32 v3, v16 offset:2112
	ds_write_b32 v3, v17 offset:2116
	ds_write_b32 v3, v18 offset:2120
	ds_write_b32 v3, v19 offset:2124
	ds_write_b32 v3, v20 offset:3168
	ds_write_b32 v3, v21 offset:3172
	ds_write_b32 v3, v22 offset:3176
	ds_write_b32 v3, v23 offset:3180
	ds_write_b32 v3, v24 offset:4224
	ds_write_b32 v3, v25 offset:4228
	ds_write_b32 v3, v26 offset:4232
	ds_write_b32 v3, v27 offset:4236
	ds_write_b32 v3, v28 offset:5280
	ds_write_b32 v3, v29 offset:5284
	ds_write_b32 v3, v30 offset:5288
	ds_write_b32 v3, v31 offset:5292
	ds_write_b32 v3, v32 offset:6336
	ds_write_b32 v3, v33 offset:6340
	ds_write_b32 v3, v34 offset:6344
	ds_write_b32 v3, v35 offset:6348
	ds_write_b32 v3, v36 offset:7392
	ds_write_b32 v3, v37 offset:7396
	ds_write_b32 v3, v38 offset:7400
	ds_write_b32 v3, v39 offset:7404
	s_mov_b32 s32, s2
	s_mov_b32 s33, s3
	s_lshl_b32 s49, s7, 3
	v_mad_u32_u24 v6, v1, s7, v2
	s_waitcnt lgkmcnt(0)
	ds_read_b32 v72, v4 offset:0
	ds_read_b32 v73, v4 offset:132
	ds_read_b32 v74, v4 offset:264
	ds_read_b32 v75, v4 offset:396
	ds_read_b32 v76, v4 offset:528
	ds_read_b32 v77, v4 offset:660
	ds_read_b32 v78, v4 offset:792
	ds_read_b32 v79, v4 offset:924
	ds_read_b32 v80, v4 offset:32
	ds_read_b32 v81, v4 offset:164
	ds_read_b32 v82, v4 offset:296
	ds_read_b32 v83, v4 offset:428
	ds_read_b32 v84, v4 offset:560
	ds_read_b32 v85, v4 offset:692
	ds_read_b32 v86, v4 offset:824
	ds_read_b32 v87, v4 offset:956
	s_waitcnt lgkmcnt(8)
	v_cvt_pk_bf16_f32 v104, v72, v73
	v_cvt_pk_bf16_f32 v105, v74, v75
	v_cvt_pk_bf16_f32 v106, v76, v77
	v_cvt_pk_bf16_f32 v107, v78, v79
	global_store_dwordx4 v6, v[104:107], s[32:33] nt
	s_add_u32 s32, s32, s49
	s_addc_u32 s33, s33, 0
	ds_read_b32 v88, v4 offset:64
	ds_read_b32 v89, v4 offset:196
	ds_read_b32 v90, v4 offset:328
	ds_read_b32 v91, v4 offset:460
	ds_read_b32 v92, v4 offset:592
	ds_read_b32 v93, v4 offset:724
	ds_read_b32 v94, v4 offset:856
	ds_read_b32 v95, v4 offset:988
	s_waitcnt lgkmcnt(8)
	v_cvt_pk_bf16_f32 v108, v80, v81
	v_cvt_pk_bf16_f32 v109, v82, v83
	v_cvt_pk_bf16_f32 v110, v84, v85
	v_cvt_pk_bf16_f32 v111, v86, v87
	global_store_dwordx4 v6, v[108:111], s[32:33] nt
	s_add_u32 s32, s32, s49
	s_addc_u32 s33, s33, 0
	ds_read_b32 v96, v4 offset:96
	ds_read_b32 v97, v4 offset:228
	ds_read_b32 v98, v4 offset:360
	ds_read_b32 v99, v4 offset:492
	ds_read_b32 v100, v4 offset:624
	ds_read_b32 v101, v4 offset:756
	ds_read_b32 v102, v4 offset:888
	ds_read_b32 v103, v4 offset:1020
	s_waitcnt lgkmcnt(8)
	v_cvt_pk_bf16_f32 v112, v88, v89
	v_cvt_pk_bf16_f32 v113, v90, v91
	v_cvt_pk_bf16_f32 v114, v92, v93
	v_cvt_pk_bf16_f32 v115, v94, v95
	global_store_dwordx4 v6, v[112:115], s[32:33] nt
	s_add_u32 s32, s32, s49
	s_addc_u32 s33, s33, 0
	s_waitcnt lgkmcnt(0)
	v_cvt_pk_bf16_f32 v116, v96, v97
	v_cvt_pk_bf16_f32 v117, v98, v99
	v_cvt_pk_bf16_f32 v118, v100, v101
	v_cvt_pk_bf16_f32 v119, v102, v103
	global_store_dwordx4 v6, v[116:119], s[32:33] nt
	s_add_u32 s32, s32, s49
	s_addc_u32 s33, s33, 0
	s_branch .Ltt2_done
.Ltt2_lastA:
	s_waitcnt vmcnt(4)
	ds_write_b32 v3, v8 offset:0
	ds_write_b32 v3, v9 offset:4
	ds_write_b32 v3, v10 offset:8
	ds_write_b32 v3, v11 offset:12
	ds_write_b32 v3, v12 offset:1056
	ds_write_b32 v3, v13 offset:1060
	ds_write_b32 v3, v14 offset:1064
	ds_write_b32 v3, v15 offset:1068
	ds_write_b32 v3, v16 offset:2112
	ds_write_b32 v3, v17 offset:2116
	ds_write_b32 v3, v18 offset:2120
	ds_write_b32 v3, v19 offset:2124
	ds_write_b32 v3, v20 offset:3168
	ds_write_b32 v3, v21 offset:3172
	ds_write_b32 v3, v22 offset:3176
	ds_write_b32 v3, v23 offset:3180
	ds_write_b32 v3, v24 offset:4224
	ds_write_b32 v3, v25 offset:4228
	ds_write_b32 v3, v26 offset:4232
	ds_write_b32 v3, v27 offset:4236
	ds_write_b32 v3, v28 offset:5280
	ds_write_b32 v3, v29 offset:5284
	ds_write_b32 v3, v30 offset:5288
	ds_write_b32 v3, v31 offset:5292
	ds_write_b32 v3, v32 offset:6336
	ds_write_b32 v3, v33 offset:6340
	ds_write_b32 v3, v34 offset:6344
	ds_write_b32 v3, v35 offset:6348
	ds_write_b32 v3, v36 offset:7392
	ds_write_b32 v3, v37 offset:7396
	ds_write_b32 v3, v38 offset:7400
	ds_write_b32 v3, v39 offset:7404
	s_mov_b32 s32, s2
	s_mov_b32 s33, s3
	s_lshl_b32 s49, s7, 3
	v_mad_u32_u24 v6, v1, s7, v2
	s_waitcnt lgkmcnt(0)
	ds_read_b32 v72, v4 offset:0
	ds_read_b32 v73, v4 offset:132
	ds_read_b32 v74, v4 offset:264
	ds_read_b32 v75, v4 offset:396
	ds_read_b32 v76, v4 offset:528
	ds_read_b32 v77, v4 offset:660
	ds_read_b32 v78, v4 offset:792
	ds_read_b32 v79, v4 offset:924
	ds_read_b32 v80, v4 offset:32
	ds_read_b32 v81, v4 offset:164
	ds_read_b32 v82, v4 offset:296
	ds_read_b32 v83, v4 offset:428
	ds_read_b32 v84, v4 offset:560
	ds_read_b32 v85, v4 offset:692
	ds_read_b32 v86, v4 offset:824
	ds_read_b32 v87, v4 offset:956
	s_waitcnt lgkmcnt(8)
	v_cvt_pk_bf16_f32 v104, v72, v73
	v_cvt_pk_bf16_f32 v105, v74, v75
	v_cvt_pk_bf16_f32 v106, v76, v77
	v_cvt_pk_bf16_f32 v107, v78, v79
	global_store_dwordx4 v6, v[104:107], s[32:33] nt
	s_add_u32 s32, s32, s49
	s_addc_u32 s33, s33, 0
	ds_read_b32 v88, v4 offset:64
	ds_read_b32 v89, v4 offset:196
	ds_read_b32 v90, v4 offset:328
	ds_read_b32 v91, v4 offset:460
	ds_read_b32 v92, v4 offset:592
	ds_read_b32 v93, v4 offset:724
	ds_read_b32 v94, v4 offset:856
	ds_read_b32 v95, v4 offset:988
	s_waitcnt lgkmcnt(8)
	v_cvt_pk_bf16_f32 v108, v80, v81
	v_cvt_pk_bf16_f32 v109, v82, v83
	v_cvt_pk_bf16_f32 v110, v84, v85
	v_cvt_pk_bf16_f32 v111, v86, v87
	global_store_dwordx4 v6, v[108:111], s[32:33] nt
	s_add_u32 s32, s32, s49
	s_addc_u32 s33, s33, 0
	ds_read_b32 v96, v4 offset:96
	ds_read_b32 v97, v4 offset:228
	ds_read_b32 v98, v4 offset:360
	ds_read_b32 v99, v4 offset:492
	ds_read_b32 v100, v4 offset:624
	ds_read_b32 v101, v4 offset:756
	ds_read_b32 v102, v4 offset:888
	ds_read_b32 v103, v4 offset:1020
	s_waitcnt lgkmcnt(8)
	v_cvt_pk_bf16_f32 v112, v88, v89
	v_cvt_pk_bf16_f32 v113, v90, v91
	v_cvt_pk_bf16_f32 v114, v92, v93
	v_cvt_pk_bf16_f32 v115, v94, v95
	global_store_dwordx4 v6, v[112:115], s[32:33] nt
	s_add_u32 s32, s32, s49
	s_addc_u32 s33, s33, 0
	s_waitcnt lgkmcnt(0)
	v_cvt_pk_bf16_f32 v116, v96, v97
	v_cvt_pk_bf16_f32 v117, v98, v99
	v_cvt_pk_bf16_f32 v118, v100, v101
	v_cvt_pk_bf16_f32 v119, v102, v103
	global_store_dwordx4 v6, v[116:119], s[32:33] nt
	s_add_u32 s32, s32, s49
	s_addc_u32 s33, s33, 0
	s_branch .Ltt2_done
.Ltt2_lastB:
	s_waitcnt vmcnt(4)
	ds_write_b32 v3, v40 offset:0
	ds_write_b32 v3, v41 offset:4
	ds_write_b32 v3, v42 offset:8
	ds_write_b32 v3, v43 offset:12
	ds_write_b32 v3, v44 offset:1056
	ds_write_b32 v3, v45 offset:1060
	ds_write_b32 v3, v46 offset:1064
	ds_write_b32 v3, v47 offset:1068
	ds_write_b32 v3, v48 offset:2112
	ds_write_b32 v3, v49 offset:2116
	ds_write_b32 v3, v50 offset:2120
	ds_write_b32 v3, v51 offset:2124
	ds_write_b32 v3, v52 offset:3168
	ds_write_b32 v3, v53 offset:3172
	ds_write_b32 v3, v54 offset:3176
	ds_write_b32 v3, v55 offset:3180
	ds_write_b32 v3, v56 offset:4224
	ds_write_b32 v3, v57 offset:4228
	ds_write_b32 v3, v58 offset:4232
	ds_write_b32 v3, v59 offset:4236
	ds_write_b32 v3, v60 offset:5280
	ds_write_b32 v3, v61 offset:5284
	ds_write_b32 v3, v62 offset:5288
	ds_write_b32 v3, v63 offset:5292
	ds_write_b32 v3, v64 offset:6336
	ds_write_b32 v3, v65 offset:6340
	ds_write_b32 v3, v66 offset:6344
	ds_write_b32 v3, v67 offset:6348
	ds_write_b32 v3, v68 offset:7392
	ds_write_b32 v3, v69 offset:7396
	ds_write_b32 v3, v70 offset:7400
	ds_write_b32 v3, v71 offset:7404
	s_mov_b32 s32, s10
	s_mov_b32 s33, s11
	s_lshl_b32 s49, s47, 3
	v_mad_u32_u24 v6, v1, s47, v2
	s_waitcnt lgkmcnt(0)
	ds_read_b32 v72, v4 offset:0
	ds_read_b32 v73, v4 offset:132
	ds_read_b32 v74, v4 offset:264
	ds_read_b32 v75, v4 offset:396
	ds_read_b32 v76, v4 offset:528
	ds_read_b32 v77, v4 offset:660
	ds_read_b32 v78, v4 offset:792
	ds_read_b32 v79, v4 offset:924
	ds_read_b32 v80, v4 offset:32
	ds_read_b32 v81, v4 offset:164
	ds_read_b32 v82, v4 offset:296
	ds_read_b32 v83, v4 offset:428
	ds_read_b32 v84, v4 offset:560
	ds_read_b32 v85, v4 offset:692
	ds_read_b32 v86, v4 offset:824
	ds_read_b32 v87, v4 offset:956
	s_waitcnt lgkmcnt(8)
	v_cvt_pk_bf16_f32 v104, v72, v73
	v_cvt_pk_bf16_f32 v105, v74, v75
	v_cvt_pk_bf16_f32 v106, v76, v77
	v_cvt_pk_bf16_f32 v107, v78, v79
	global_store_dwordx4 v6, v[104:107], s[32:33] nt
	s_add_u32 s32, s32, s49
	s_addc_u32 s33, s33, 0
	ds_read_b32 v88, v4 offset:64
	ds_read_b32 v89, v4 offset:196
	ds_read_b32 v90, v4 offset:328
	ds_read_b32 v91, v4 offset:460
	ds_read_b32 v92, v4 offset:592
	ds_read_b32 v93, v4 offset:724
	ds_read_b32 v94, v4 offset:856
	ds_read_b32 v95, v4 offset:988
	s_waitcnt lgkmcnt(8)
	v_cvt_pk_bf16_f32 v108, v80, v81
	v_cvt_pk_bf16_f32 v109, v82, v83
	v_cvt_pk_bf16_f32 v110, v84, v85
	v_cvt_pk_bf16_f32 v111, v86, v87
	global_store_dwordx4 v6, v[108:111], s[32:33] nt
	s_add_u32 s32, s32, s49
	s_addc_u32 s33, s33, 0
	ds_read_b32 v96, v4 offset:96
	ds_read_b32 v97, v4 offset:228
	ds_read_b32 v98, v4 offset:360
	ds_read_b32 v99, v4 offset:492
	ds_read_b32 v100, v4 offset:624
	ds_read_b32 v101, v4 offset:756
	ds_read_b32 v102, v4 offset:888
	ds_read_b32 v103, v4 offset:1020
	s_waitcnt lgkmcnt(8)
	v_cvt_pk_bf16_f32 v112, v88, v89
	v_cvt_pk_bf16_f32 v113, v90, v91
	v_cvt_pk_bf16_f32 v114, v92, v93
	v_cvt_pk_bf16_f32 v115, v94, v95
	global_store_dwordx4 v6, v[112:115], s[32:33] nt
	s_add_u32 s32, s32, s49
	s_addc_u32 s33, s33, 0
	s_waitcnt lgkmcnt(0)
	v_cvt_pk_bf16_f32 v116, v96, v97
	v_cvt_pk_bf16_f32 v117, v98, v99
	v_cvt_pk_bf16_f32 v118, v100, v101
	v_cvt_pk_bf16_f32 v119, v102, v103
	global_store_dwordx4 v6, v[116:119], s[32:33] nt
	s_add_u32 s32, s32, s49
	s_addc_u32 s33, s33, 0
.Ltt2_done:
	s_cmp_lt_i32 s79, 4
	s_cbranch_scc1 .LBB0_418

.LBB0_832:
	s_waitcnt vmcnt(0)
	s_barrier
	s_cmp_lg_u32 s87, 0x100
	s_cbranch_scc1 .Ltt7_done
	s_cmp_lt_u32 s96, 128
	s_cbranch_scc1 .Ltt7_done
	s_sub_u32 s20, s96, 128
	s_lshl_b32 s20, s20, 3
	s_add_u32 s20, s20, s93
	s_movk_i32 s23, 1024
	v_mbcnt_hi_u32_b32 v0, -1, v212
	v_and_b32_e32 v0, 63, v0
	v_lshrrev_b32_e32 v1, 3, v0
	v_and_b32_e32 v2, 7, v0
	s_lshl_b32 s25, s93, 14
	v_mul_u32_u24_e32 v3, 0x84, v1
	v_mul_u32_u24_e32 v4, 0x420, v2
	v_lshlrev_b32_e32 v2, 4, v2
	v_add3_u32 v3, v3, v2, s25
	v_lshl_add_u32 v4, v1, 2, v4
	v_add_u32_e32 v4, s25, v4
	v_readlane_b32 s62, v244, 21
	v_readlane_b32 s63, v244, 22
	s_add_u32 s64, s76, 0x8989000
	s_addc_u32 s65, s77, 0
	v_readlane_b32 s66, v245, 0
	v_readlane_b32 s67, v245, 1
	s_add_u32 s68, s76, 0x6989000
	s_addc_u32 s69, s77, 0
	s_nop 0
	s_add_u32 s66, s66, 0x4000000
	s_addc_u32 s67, s67, 0
	s_cmp_ge_u32 s20, 12288
	s_cbranch_scc1 .Ltt7_done
	s_cmp_lt_u32 s20, 4096
	s_cbranch_scc1 .Ltt7_r1_s0
	s_sub_u32 s25, s20, 4096
	s_lshr_b32 s27, s25, 8
	s_and_b32 s31, s25, 255
	s_mul_i32 s35, s27, 0x200000
	s_lshl_b32 s41, s31, 7
	s_add_u32 s35, s35, s41
	s_add_u32 s0, s66, s35
	s_addc_u32 s1, s67, 0
	s_mul_i32 s35, s31, 0x20000
	s_lshl_b32 s41, s27, 7
	s_add_u32 s35, s35, s41
	s_add_u32 s2, s68, s35
	s_addc_u32 s3, s69, 0
	s_mov_b32 s5, 0x8000
	s_mov_b32 s6, 0x40000
	s_mov_b32 s7, 0x1000
	s_branch .Ltt7_r1_e
.Ltt7_r1_s0:
	s_sub_u32 s25, s20, -4096
	s_lshr_b32 s27, s25, 6
	s_and_b32 s31, s25, 63
	s_mul_i32 s35, s27, 0x80000
	s_lshl_b32 s41, s31, 7
	s_add_u32 s35, s35, s41
	s_add_u32 s0, s62, s35
	s_addc_u32 s1, s63, 0
	s_mul_i32 s35, s31, 0x80000
	s_lshl_b32 s41, s27, 7
	s_add_u32 s35, s35, s41
	s_add_u32 s2, s64, s35
	s_addc_u32 s3, s65, 0
	s_mov_b32 s5, 0x2000
	s_mov_b32 s6, 0x10000
	s_mov_b32 s7, 0x4000
.Ltt7_r1_e:
	v_mad_u32_u24 v5, v1, s5, v2
	global_load_dwordx4 v[8:11], v5, s[0:1] nt
	s_add_u32 s0, s0, s6
	s_addc_u32 s1, s1, 0
	global_load_dwordx4 v[12:15], v5, s[0:1] nt
	s_add_u32 s0, s0, s6
	s_addc_u32 s1, s1, 0
	global_load_dwordx4 v[16:19], v5, s[0:1] nt
	s_add_u32 s0, s0, s6
	s_addc_u32 s1, s1, 0
	global_load_dwordx4 v[20:23], v5, s[0:1] nt
	s_add_u32 s0, s0, s6
	s_addc_u32 s1, s1, 0
	global_load_dwordx4 v[24:27], v5, s[0:1] nt
	s_add_u32 s0, s0, s6
	s_addc_u32 s1, s1, 0
	global_load_dwordx4 v[28:31], v5, s[0:1] nt
	s_add_u32 s0, s0, s6
	s_addc_u32 s1, s1, 0
	global_load_dwordx4 v[32:35], v5, s[0:1] nt
	s_add_u32 s0, s0, s6
	s_addc_u32 s1, s1, 0
	global_load_dwordx4 v[36:39], v5, s[0:1] nt
	s_add_u32 s0, s0, s6
	s_addc_u32 s1, s1, 0
	s_add_u32 s20, s20, s23
	s_cmp_ge_u32 s20, 12288
	s_cbranch_scc1 .Ltt7_lastA0
	s_cmp_lt_u32 s20, 4096
	s_cbranch_scc1 .Ltt7_r2_s0
	s_sub_u32 s25, s20, 4096
	s_lshr_b32 s27, s25, 8
	s_and_b32 s31, s25, 255
	s_mul_i32 s35, s27, 0x200000
	s_lshl_b32 s41, s31, 7
	s_add_u32 s35, s35, s41
	s_add_u32 s0, s66, s35
	s_addc_u32 s1, s67, 0
	s_mul_i32 s35, s31, 0x20000
	s_lshl_b32 s41, s27, 7
	s_add_u32 s35, s35, s41
	s_add_u32 s10, s68, s35
	s_addc_u32 s11, s69, 0
	s_mov_b32 s5, 0x8000
	s_mov_b32 s6, 0x40000
	s_mov_b32 s47, 0x1000
	s_branch .Ltt7_r2_e
.Ltt7_r2_s0:
	s_sub_u32 s25, s20, -4096
	s_lshr_b32 s27, s25, 6
	s_and_b32 s31, s25, 63
	s_mul_i32 s35, s27, 0x80000
	s_lshl_b32 s41, s31, 7
	s_add_u32 s35, s35, s41
	s_add_u32 s0, s62, s35
	s_addc_u32 s1, s63, 0
	s_mul_i32 s35, s31, 0x80000
	s_lshl_b32 s41, s27, 7
	s_add_u32 s35, s35, s41
	s_add_u32 s10, s64, s35
	s_addc_u32 s11, s65, 0
	s_mov_b32 s5, 0x2000
	s_mov_b32 s6, 0x10000
	s_mov_b32 s47, 0x4000

.Ltt7_loop:
	s_add_u32 s20, s20, s23
	s_cmp_ge_u32 s20, 12288
	s_cbranch_scc1 .Ltt7_lastB
	s_cmp_lt_u32 s20, 4096
	s_cbranch_scc1 .Ltt7_r3_s0
	s_sub_u32 s25, s20, 4096
	s_lshr_b32 s27, s25, 8
	s_and_b32 s31, s25, 255
	s_mul_i32 s35, s27, 0x200000
	s_lshl_b32 s41, s31, 7
	s_add_u32 s35, s35, s41
	s_add_u32 s0, s66, s35
	s_addc_u32 s1, s67, 0
	s_mul_i32 s35, s31, 0x20000
	s_lshl_b32 s41, s27, 7
	s_add_u32 s35, s35, s41
	s_add_u32 s2, s68, s35
	s_addc_u32 s3, s69, 0
	s_mov_b32 s5, 0x8000
	s_mov_b32 s6, 0x40000
	s_mov_b32 s7, 0x1000
	s_branch .Ltt7_r3_e

.Ltt7_r3_e:
	v_mad_u32_u24 v5, v1, s5, v2
	global_load_dwordx4 v[8:11], v5, s[0:1] nt
	s_add_u32 s0, s0, s6
	s_addc_u32 s1, s1, 0
	global_load_dwordx4 v[12:15], v5, s[0:1] nt
	s_add_u32 s0, s0, s6
	s_addc_u32 s1, s1, 0
	global_load_dwordx4 v[16:19], v5, s[0:1] nt
	s_add_u32 s0, s0, s6
	s_addc_u32 s1, s1, 0
	global_load_dwordx4 v[20:23], v5, s[0:1] nt
	s_add_u32 s0, s0, s6
	s_addc_u32 s1, s1, 0
	global_load_dwordx4 v[24:27], v5, s[0:1] nt
	s_add_u32 s0, s0, s6
	s_addc_u32 s1, s1, 0
	global_load_dwordx4 v[28:31], v5, s[0:1] nt
	s_add_u32 s0, s0, s6
	s_addc_u32 s1, s1, 0
	global_load_dwordx4 v[32:35], v5, s[0:1] nt
	s_add_u32 s0, s0, s6
	s_addc_u32 s1, s1, 0
	global_load_dwordx4 v[36:39], v5, s[0:1] nt
	s_add_u32 s0, s0, s6
	s_addc_u32 s1, s1, 0
	s_waitcnt vmcnt(12)
	ds_write_b32 v3, v40 offset:0
	ds_write_b32 v3, v41 offset:4
	ds_write_b32 v3, v42 offset:8
	ds_write_b32 v3, v43 offset:12
	ds_write_b32 v3, v44 offset:1056
	ds_write_b32 v3, v45 offset:1060
	ds_write_b32 v3, v46 offset:1064
	ds_write_b32 v3, v47 offset:1068
	ds_write_b32 v3, v48 offset:2112
	ds_write_b32 v3, v49 offset:2116
	ds_write_b32 v3, v50 offset:2120
	ds_write_b32 v3, v51 offset:2124
	ds_write_b32 v3, v52 offset:3168
	ds_write_b32 v3, v53 offset:3172
	ds_write_b32 v3, v54 offset:3176
	ds_write_b32 v3, v55 offset:3180
	ds_write_b32 v3, v56 offset:4224
	ds_write_b32 v3, v57 offset:4228
	ds_write_b32 v3, v58 offset:4232
	ds_write_b32 v3, v59 offset:4236
	ds_write_b32 v3, v60 offset:5280
	ds_write_b32 v3, v61 offset:5284
	ds_write_b32 v3, v62 offset:5288
	ds_write_b32 v3, v63 offset:5292
	ds_write_b32 v3, v64 offset:6336
	ds_write_b32 v3, v65 offset:6340
	ds_write_b32 v3, v66 offset:6344
	ds_write_b32 v3, v67 offset:6348
	ds_write_b32 v3, v68 offset:7392
	ds_write_b32 v3, v69 offset:7396
	ds_write_b32 v3, v70 offset:7400
	ds_write_b32 v3, v71 offset:7404
	s_mov_b32 s32, s10
	s_mov_b32 s33, s11
	s_lshl_b32 s49, s47, 3
	v_mad_u32_u24 v6, v1, s47, v2
	s_waitcnt lgkmcnt(0)
	ds_read_b32 v72, v4 offset:0
	ds_read_b32 v73, v4 offset:132
	ds_read_b32 v74, v4 offset:264
	ds_read_b32 v75, v4 offset:396
	ds_read_b32 v76, v4 offset:528
	ds_read_b32 v77, v4 offset:660
	ds_read_b32 v78, v4 offset:792
	ds_read_b32 v79, v4 offset:924
	ds_read_b32 v80, v4 offset:32
	ds_read_b32 v81, v4 offset:164
	ds_read_b32 v82, v4 offset:296
	ds_read_b32 v83, v4 offset:428
	ds_read_b32 v84, v4 offset:560
	ds_read_b32 v85, v4 offset:692
	ds_read_b32 v86, v4 offset:824
	ds_read_b32 v87, v4 offset:956
	s_waitcnt lgkmcnt(8)
	v_cvt_pk_bf16_f32 v104, v72, v73
	v_cvt_pk_bf16_f32 v105, v74, v75
	v_cvt_pk_bf16_f32 v106, v76, v77
	v_cvt_pk_bf16_f32 v107, v78, v79
	global_store_dwordx4 v6, v[104:107], s[32:33] nt
	s_add_u32 s32, s32, s49
	s_addc_u32 s33, s33, 0
	ds_read_b32 v88, v4 offset:64
	ds_read_b32 v89, v4 offset:196
	ds_read_b32 v90, v4 offset:328
	ds_read_b32 v91, v4 offset:460
	ds_read_b32 v92, v4 offset:592
	ds_read_b32 v93, v4 offset:724
	ds_read_b32 v94, v4 offset:856
	ds_read_b32 v95, v4 offset:988
	s_waitcnt lgkmcnt(8)
	v_cvt_pk_bf16_f32 v108, v80, v81
	v_cvt_pk_bf16_f32 v109, v82, v83
	v_cvt_pk_bf16_f32 v110, v84, v85
	v_cvt_pk_bf16_f32 v111, v86, v87
	global_store_dwordx4 v6, v[108:111], s[32:33] nt
	s_add_u32 s32, s32, s49
	s_addc_u32 s33, s33, 0
	ds_read_b32 v96, v4 offset:96
	ds_read_b32 v97, v4 offset:228
	ds_read_b32 v98, v4 offset:360
	ds_read_b32 v99, v4 offset:492
	ds_read_b32 v100, v4 offset:624
	ds_read_b32 v101, v4 offset:756
	ds_read_b32 v102, v4 offset:888
	ds_read_b32 v103, v4 offset:1020
	s_waitcnt lgkmcnt(8)
	v_cvt_pk_bf16_f32 v112, v88, v89
	v_cvt_pk_bf16_f32 v113, v90, v91
	v_cvt_pk_bf16_f32 v114, v92, v93
	v_cvt_pk_bf16_f32 v115, v94, v95
	global_store_dwordx4 v6, v[112:115], s[32:33] nt
	s_add_u32 s32, s32, s49
	s_addc_u32 s33, s33, 0
	s_waitcnt lgkmcnt(0)
	v_cvt_pk_bf16_f32 v116, v96, v97
	v_cvt_pk_bf16_f32 v117, v98, v99
	v_cvt_pk_bf16_f32 v118, v100, v101
	v_cvt_pk_bf16_f32 v119, v102, v103
	global_store_dwordx4 v6, v[116:119], s[32:33] nt
	s_add_u32 s32, s32, s49
	s_addc_u32 s33, s33, 0
	s_add_u32 s20, s20, s23
	s_cmp_ge_u32 s20, 12288
	s_cbranch_scc1 .Ltt7_lastA
	s_cmp_lt_u32 s20, 4096
	s_cbranch_scc1 .Ltt7_r4_s0
	s_sub_u32 s25, s20, 4096
	s_lshr_b32 s27, s25, 8
	s_and_b32 s31, s25, 255
	s_mul_i32 s35, s27, 0x200000
	s_lshl_b32 s41, s31, 7
	s_add_u32 s35, s35, s41
	s_add_u32 s0, s66, s35
	s_addc_u32 s1, s67, 0
	s_mul_i32 s35, s31, 0x20000
	s_lshl_b32 s41, s27, 7
	s_add_u32 s35, s35, s41
	s_add_u32 s10, s68, s35
	s_addc_u32 s11, s69, 0
	s_mov_b32 s5, 0x8000
	s_mov_b32 s6, 0x40000
	s_mov_b32 s47, 0x1000
	s_branch .Ltt7_r4_e

.Ltt7_done:
.LBB0_833:
	s_cmp_lt_i32 s79, 9
	s_cbranch_scc1 .LBB0_888
	s_waitcnt vmcnt(0)
	v_readlane_b32 s0, v244, 1
	v_cmp_eq_u32_e32 vcc, 0, v146
	v_readlane_b32 s1, v244, 2
	v_readlane_b32 s5, v244, 51
	v_readlane_b32 s4, v244, 52
	s_and_b64 s[2:3], s[0:1], vcc
	v_mov_b32_e32 v2, s5
	v_mov_b32_e32 v3, s4
	s_waitcnt vmcnt(0)
	s_barrier
	s_and_saveexec_b64 s[0:1], s[2:3]
	s_cbranch_execz .LBB0_887
	s_cmp_lg_u32 s4, 0
	v_mov_b32_e32 v2, s5
	v_mov_b32_e32 v3, s4
	s_cbranch_scc1 .LBB0_850
	s_add_u32 s2, s76, 0x1000
	s_addc_u32 s3, s77, 0
	s_add_u32 s4, s76, 0x1100
	s_addc_u32 s5, s77, 0
	s_add_u32 s6, s76, 0x1200
	s_addc_u32 s7, s77, 0
	s_add_u32 s10, s76, 0x1300
	s_addc_u32 s11, s77, 0
	s_mov_b32 s18, 1
	v_mov_b32_e32 v16, 0
	s_branch .LBB0_838

.LBB0_1154:
	s_waitcnt vmcnt(0)
	s_barrier
	s_cmp_lg_u32 s87, 0x100
	s_cbranch_scc1 .Ltt10_done
	s_cmp_lt_u32 s96, 96
	s_cbranch_scc1 .Ltt10_done
	s_sub_u32 s20, s96, 96
	s_lshl_b32 s20, s20, 3
	s_add_u32 s20, s20, s93
	s_movk_i32 s23, 1280
	v_mbcnt_hi_u32_b32 v0, -1, v212
	v_and_b32_e32 v0, 63, v0
	v_lshrrev_b32_e32 v1, 3, v0
	v_and_b32_e32 v2, 7, v0
	s_lshl_b32 s25, s93, 14
	v_mul_u32_u24_e32 v3, 0x84, v1
	v_mul_u32_u24_e32 v4, 0x420, v2
	v_lshlrev_b32_e32 v2, 4, v2
	v_add3_u32 v3, v3, v2, s25
	v_lshl_add_u32 v4, v1, 2, v4
	v_add_u32_e32 v4, s25, v4
	v_readlane_b32 s62, v244, 39
	v_readlane_b32 s63, v244, 40
	s_add_u32 s64, s76, 0x4189000
	s_addc_u32 s65, s77, 0
	v_readlane_b32 s66, v244, 21
	v_readlane_b32 s67, v244, 22
	s_add_u32 s68, s76, 0xa989000
	s_addc_u32 s69, s77, 0
	s_nop 0
	s_add_u32 s66, s66, 0x4000000
	s_addc_u32 s67, s67, 0
	s_cmp_ge_u32 s20, 10240
	s_cbranch_scc1 .Ltt10_done
	s_cmp_lt_u32 s20, 2048
	s_cbranch_scc1 .Ltt10_r1_s0
	s_sub_u32 s25, s20, 2048
	s_lshr_b32 s27, s25, 6
	s_and_b32 s31, s25, 63
	s_mul_i32 s35, s27, 0x80000
	s_lshl_b32 s41, s31, 7
	s_add_u32 s35, s35, s41
	s_add_u32 s0, s66, s35
	s_addc_u32 s1, s67, 0
	s_mul_i32 s35, s31, 0x80000
	s_lshl_b32 s41, s27, 7
	s_add_u32 s35, s35, s41
	s_add_u32 s2, s68, s35
	s_addc_u32 s3, s69, 0
	s_mov_b32 s5, 0x2000
	s_mov_b32 s6, 0x10000
	s_mov_b32 s7, 0x4000
	s_branch .Ltt10_r1_e
.Ltt10_r1_s0:
	s_sub_u32 s25, s20, 0
	s_lshr_b32 s27, s25, 6
	s_and_b32 s31, s25, 63
	s_mul_i32 s35, s27, 0x80000
	s_lshl_b32 s41, s31, 7
	s_add_u32 s35, s35, s41
	s_add_u32 s0, s62, s35
	s_addc_u32 s1, s63, 0
	s_mul_i32 s35, s31, 0x20000
	s_lshl_b32 s41, s27, 7
	s_add_u32 s35, s35, s41
	s_add_u32 s2, s64, s35
	s_addc_u32 s3, s65, 0
	s_mov_b32 s5, 0x2000
	s_mov_b32 s6, 0x10000
	s_mov_b32 s7, 0x1000
.Ltt10_r1_e:
	v_mad_u32_u24 v5, v1, s5, v2
	global_load_dwordx4 v[8:11], v5, s[0:1] nt
	s_add_u32 s0, s0, s6
	s_addc_u32 s1, s1, 0
	global_load_dwordx4 v[12:15], v5, s[0:1] nt
	s_add_u32 s0, s0, s6
	s_addc_u32 s1, s1, 0
	global_load_dwordx4 v[16:19], v5, s[0:1] nt
	s_add_u32 s0, s0, s6
	s_addc_u32 s1, s1, 0
	global_load_dwordx4 v[20:23], v5, s[0:1] nt
	s_add_u32 s0, s0, s6
	s_addc_u32 s1, s1, 0
	global_load_dwordx4 v[24:27], v5, s[0:1] nt
	s_add_u32 s0, s0, s6
	s_addc_u32 s1, s1, 0
	global_load_dwordx4 v[28:31], v5, s[0:1] nt
	s_add_u32 s0, s0, s6
	s_addc_u32 s1, s1, 0
	global_load_dwordx4 v[32:35], v5, s[0:1] nt
	s_add_u32 s0, s0, s6
	s_addc_u32 s1, s1, 0
	global_load_dwordx4 v[36:39], v5, s[0:1] nt
	s_add_u32 s0, s0, s6
	s_addc_u32 s1, s1, 0
	s_add_u32 s20, s20, s23
	s_cmp_ge_u32 s20, 10240
	s_cbranch_scc1 .Ltt10_lastA0
	s_cmp_lt_u32 s20, 2048
	s_cbranch_scc1 .Ltt10_r2_s0
	s_sub_u32 s25, s20, 2048
	s_lshr_b32 s27, s25, 6
	s_and_b32 s31, s25, 63
	s_mul_i32 s35, s27, 0x80000
	s_lshl_b32 s41, s31, 7
	s_add_u32 s35, s35, s41
	s_add_u32 s0, s66, s35
	s_addc_u32 s1, s67, 0
	s_mul_i32 s35, s31, 0x80000
	s_lshl_b32 s41, s27, 7
	s_add_u32 s35, s35, s41
	s_add_u32 s10, s68, s35
	s_addc_u32 s11, s69, 0
	s_mov_b32 s5, 0x2000
	s_mov_b32 s6, 0x10000
	s_mov_b32 s47, 0x4000
	s_branch .Ltt10_r2_e
.Ltt10_r2_s0:
	s_sub_u32 s25, s20, 0
	s_lshr_b32 s27, s25, 6
	s_and_b32 s31, s25, 63
	s_mul_i32 s35, s27, 0x80000
	s_lshl_b32 s41, s31, 7
	s_add_u32 s35, s35, s41
	s_add_u32 s0, s62, s35
	s_addc_u32 s1, s63, 0
	s_mul_i32 s35, s31, 0x20000
	s_lshl_b32 s41, s27, 7
	s_add_u32 s35, s35, s41
	s_add_u32 s10, s64, s35
	s_addc_u32 s11, s65, 0
	s_mov_b32 s5, 0x2000
	s_mov_b32 s6, 0x10000
	s_mov_b32 s47, 0x1000

.Ltt10_loop:
	s_add_u32 s20, s20, s23
	s_cmp_ge_u32 s20, 10240
	s_cbranch_scc1 .Ltt10_lastB
	s_cmp_lt_u32 s20, 2048
	s_cbranch_scc1 .Ltt10_r3_s0
	s_sub_u32 s25, s20, 2048
	s_lshr_b32 s27, s25, 6
	s_and_b32 s31, s25, 63
	s_mul_i32 s35, s27, 0x80000
	s_lshl_b32 s41, s31, 7
	s_add_u32 s35, s35, s41
	s_add_u32 s0, s66, s35
	s_addc_u32 s1, s67, 0
	s_mul_i32 s35, s31, 0x80000
	s_lshl_b32 s41, s27, 7
	s_add_u32 s35, s35, s41
	s_add_u32 s2, s68, s35
	s_addc_u32 s3, s69, 0
	s_mov_b32 s5, 0x2000
	s_mov_b32 s6, 0x10000
	s_mov_b32 s7, 0x4000
	s_branch .Ltt10_r3_e

.Ltt10_r3_e:
	v_mad_u32_u24 v5, v1, s5, v2
	global_load_dwordx4 v[8:11], v5, s[0:1] nt
	s_add_u32 s0, s0, s6
	s_addc_u32 s1, s1, 0
	global_load_dwordx4 v[12:15], v5, s[0:1] nt
	s_add_u32 s0, s0, s6
	s_addc_u32 s1, s1, 0
	global_load_dwordx4 v[16:19], v5, s[0:1] nt
	s_add_u32 s0, s0, s6
	s_addc_u32 s1, s1, 0
	global_load_dwordx4 v[20:23], v5, s[0:1] nt
	s_add_u32 s0, s0, s6
	s_addc_u32 s1, s1, 0
	global_load_dwordx4 v[24:27], v5, s[0:1] nt
	s_add_u32 s0, s0, s6
	s_addc_u32 s1, s1, 0
	global_load_dwordx4 v[28:31], v5, s[0:1] nt
	s_add_u32 s0, s0, s6
	s_addc_u32 s1, s1, 0
	global_load_dwordx4 v[32:35], v5, s[0:1] nt
	s_add_u32 s0, s0, s6
	s_addc_u32 s1, s1, 0
	global_load_dwordx4 v[36:39], v5, s[0:1] nt
	s_add_u32 s0, s0, s6
	s_addc_u32 s1, s1, 0
	s_waitcnt vmcnt(12)
	ds_write_b32 v3, v40 offset:0
	ds_write_b32 v3, v41 offset:4
	ds_write_b32 v3, v42 offset:8
	ds_write_b32 v3, v43 offset:12
	ds_write_b32 v3, v44 offset:1056
	ds_write_b32 v3, v45 offset:1060
	ds_write_b32 v3, v46 offset:1064
	ds_write_b32 v3, v47 offset:1068
	ds_write_b32 v3, v48 offset:2112
	ds_write_b32 v3, v49 offset:2116
	ds_write_b32 v3, v50 offset:2120
	ds_write_b32 v3, v51 offset:2124
	ds_write_b32 v3, v52 offset:3168
	ds_write_b32 v3, v53 offset:3172
	ds_write_b32 v3, v54 offset:3176
	ds_write_b32 v3, v55 offset:3180
	ds_write_b32 v3, v56 offset:4224
	ds_write_b32 v3, v57 offset:4228
	ds_write_b32 v3, v58 offset:4232
	ds_write_b32 v3, v59 offset:4236
	ds_write_b32 v3, v60 offset:5280
	ds_write_b32 v3, v61 offset:5284
	ds_write_b32 v3, v62 offset:5288
	ds_write_b32 v3, v63 offset:5292
	ds_write_b32 v3, v64 offset:6336
	ds_write_b32 v3, v65 offset:6340
	ds_write_b32 v3, v66 offset:6344
	ds_write_b32 v3, v67 offset:6348
	ds_write_b32 v3, v68 offset:7392
	ds_write_b32 v3, v69 offset:7396
	ds_write_b32 v3, v70 offset:7400
	ds_write_b32 v3, v71 offset:7404
	s_mov_b32 s32, s10
	s_mov_b32 s33, s11
	s_lshl_b32 s49, s47, 3
	v_mad_u32_u24 v6, v1, s47, v2
	s_waitcnt lgkmcnt(0)
	ds_read_b32 v72, v4 offset:0
	ds_read_b32 v73, v4 offset:132
	ds_read_b32 v74, v4 offset:264
	ds_read_b32 v75, v4 offset:396
	ds_read_b32 v76, v4 offset:528
	ds_read_b32 v77, v4 offset:660
	ds_read_b32 v78, v4 offset:792
	ds_read_b32 v79, v4 offset:924
	ds_read_b32 v80, v4 offset:32
	ds_read_b32 v81, v4 offset:164
	ds_read_b32 v82, v4 offset:296
	ds_read_b32 v83, v4 offset:428
	ds_read_b32 v84, v4 offset:560
	ds_read_b32 v85, v4 offset:692
	ds_read_b32 v86, v4 offset:824
	ds_read_b32 v87, v4 offset:956
	s_waitcnt lgkmcnt(8)
	v_cvt_pk_bf16_f32 v104, v72, v73
	v_cvt_pk_bf16_f32 v105, v74, v75
	v_cvt_pk_bf16_f32 v106, v76, v77
	v_cvt_pk_bf16_f32 v107, v78, v79
	global_store_dwordx4 v6, v[104:107], s[32:33] nt
	s_add_u32 s32, s32, s49
	s_addc_u32 s33, s33, 0
	ds_read_b32 v88, v4 offset:64
	ds_read_b32 v89, v4 offset:196
	ds_read_b32 v90, v4 offset:328
	ds_read_b32 v91, v4 offset:460
	ds_read_b32 v92, v4 offset:592
	ds_read_b32 v93, v4 offset:724
	ds_read_b32 v94, v4 offset:856
	ds_read_b32 v95, v4 offset:988
	s_waitcnt lgkmcnt(8)
	v_cvt_pk_bf16_f32 v108, v80, v81
	v_cvt_pk_bf16_f32 v109, v82, v83
	v_cvt_pk_bf16_f32 v110, v84, v85
	v_cvt_pk_bf16_f32 v111, v86, v87
	global_store_dwordx4 v6, v[108:111], s[32:33] nt
	s_add_u32 s32, s32, s49
	s_addc_u32 s33, s33, 0
	ds_read_b32 v96, v4 offset:96
	ds_read_b32 v97, v4 offset:228
	ds_read_b32 v98, v4 offset:360
	ds_read_b32 v99, v4 offset:492
	ds_read_b32 v100, v4 offset:624
	ds_read_b32 v101, v4 offset:756
	ds_read_b32 v102, v4 offset:888
	ds_read_b32 v103, v4 offset:1020
	s_waitcnt lgkmcnt(8)
	v_cvt_pk_bf16_f32 v112, v88, v89
	v_cvt_pk_bf16_f32 v113, v90, v91
	v_cvt_pk_bf16_f32 v114, v92, v93
	v_cvt_pk_bf16_f32 v115, v94, v95
	global_store_dwordx4 v6, v[112:115], s[32:33] nt
	s_add_u32 s32, s32, s49
	s_addc_u32 s33, s33, 0
	s_waitcnt lgkmcnt(0)
	v_cvt_pk_bf16_f32 v116, v96, v97
	v_cvt_pk_bf16_f32 v117, v98, v99
	v_cvt_pk_bf16_f32 v118, v100, v101
	v_cvt_pk_bf16_f32 v119, v102, v103
	global_store_dwordx4 v6, v[116:119], s[32:33] nt
	s_add_u32 s32, s32, s49
	s_addc_u32 s33, s33, 0
	s_add_u32 s20, s20, s23
	s_cmp_ge_u32 s20, 10240
	s_cbranch_scc1 .Ltt10_lastA
	s_cmp_lt_u32 s20, 2048
	s_cbranch_scc1 .Ltt10_r4_s0
	s_sub_u32 s25, s20, 2048
	s_lshr_b32 s27, s25, 6
	s_and_b32 s31, s25, 63
	s_mul_i32 s35, s27, 0x80000
	s_lshl_b32 s41, s31, 7
	s_add_u32 s35, s35, s41
	s_add_u32 s0, s66, s35
	s_addc_u32 s1, s67, 0
	s_mul_i32 s35, s31, 0x80000
	s_lshl_b32 s41, s27, 7
	s_add_u32 s35, s35, s41
	s_add_u32 s10, s68, s35
	s_addc_u32 s11, s69, 0
	s_mov_b32 s5, 0x2000
	s_mov_b32 s6, 0x10000
	s_mov_b32 s47, 0x4000
	s_branch .Ltt10_r4_e

.Ltt10_done:
	s_cmp_lt_i32 s79, 12
	s_cbranch_scc1 .LBB0_1209

	.amdhsa_kernel _Z10fwd_kernel6Params
		.amdhsa_group_segment_fixed_size 0
		.amdhsa_private_segment_fixed_size 0
		.amdhsa_kernarg_size 464
		.amdhsa_user_sgpr_count 2
		.amdhsa_user_sgpr_dispatch_ptr 0
		.amdhsa_user_sgpr_queue_ptr 0
		.amdhsa_user_sgpr_kernarg_segment_ptr 1
		.amdhsa_user_sgpr_dispatch_id 0
		.amdhsa_user_sgpr_kernarg_preload_length 0
		.amdhsa_user_sgpr_kernarg_preload_offset 0
		.amdhsa_user_sgpr_private_segment_size 0
		.amdhsa_uses_dynamic_stack 0
		.amdhsa_enable_private_segment 0
		.amdhsa_system_sgpr_workgroup_id_x 1
		.amdhsa_system_sgpr_workgroup_id_y 0
		.amdhsa_system_sgpr_workgroup_id_z 0
		.amdhsa_system_sgpr_workgroup_info 0
		.amdhsa_system_vgpr_workitem_id 2
		.amdhsa_next_free_vgpr 246
		.amdhsa_next_free_sgpr 102
		.amdhsa_accum_offset 248
		.amdhsa_reserve_vcc 1
		.amdhsa_float_round_mode_32 0
		.amdhsa_float_round_mode_16_64 0
		.amdhsa_float_denorm_mode_32 3
		.amdhsa_float_denorm_mode_16_64 3
		.amdhsa_dx10_clamp 1
		.amdhsa_ieee_mode 1
		.amdhsa_fp16_overflow 0
		.amdhsa_tg_split 0
		.amdhsa_exception_fp_ieee_invalid_op 0
		.amdhsa_exception_fp_denorm_src 0
		.amdhsa_exception_fp_ieee_div_zero 0
		.amdhsa_exception_fp_ieee_overflow 0
		.amdhsa_exception_fp_ieee_underflow 0
		.amdhsa_exception_fp_ieee_inexact 0
		.amdhsa_exception_int_div_zero 0
	.end_amdhsa_kernel

amdhsa.kernels:
  - .agpr_count:     0
    .args:
      - .offset:         0
        .size:           208
        .value_kind:     by_value
      - .offset:         208
        .size:           4
        .value_kind:     hidden_block_count_x
      - .offset:         212
        .size:           4
        .value_kind:     hidden_block_count_y
      - .offset:         216
        .size:           4
        .value_kind:     hidden_block_count_z
      - .offset:         220
        .size:           2
        .value_kind:     hidden_group_size_x
      - .offset:         222
        .size:           2
        .value_kind:     hidden_group_size_y
      - .offset:         224
        .size:           2
        .value_kind:     hidden_group_size_z
      - .offset:         226
        .size:           2
        .value_kind:     hidden_remainder_x
      - .offset:         228
        .size:           2
        .value_kind:     hidden_remainder_y
      - .offset:         230
        .size:           2
        .value_kind:     hidden_remainder_z
      - .offset:         248
        .size:           8
        .value_kind:     hidden_global_offset_x
      - .offset:         256
        .size:           8
        .value_kind:     hidden_global_offset_y
      - .offset:         264
        .size:           8
        .value_kind:     hidden_global_offset_z
      - .offset:         272
        .size:           2
        .value_kind:     hidden_grid_dims
      - .offset:         296
        .size:           8
        .value_kind:     hidden_multigrid_sync_arg
      - .offset:         328
        .size:           4
        .value_kind:     hidden_dynamic_lds_size
    .group_segment_fixed_size: 0
    .kernarg_segment_align: 8
    .kernarg_segment_size: 464
    .language:       OpenCL C
    .language_version:
      - 2
      - 0
    .max_flat_workgroup_size: 512
    .name:           _Z10fwd_kernel6Params
    .private_segment_fixed_size: 0
    .sgpr_count:     108
    .sgpr_spill_count: 137
    .symbol:         _Z10fwd_kernel6Params.kd
    .uniform_work_group_size: 1
    .uses_dynamic_stack: false
    .vgpr_count:     246
    .vgpr_spill_count: 0
    .wavefront_size: 64
